# expert-table fp8/fp4 quantisation moved out of the PEER-query GEMM phase into the score phase tile loop (row loads fly under the tile's GEMM and top-16 networks)
# speedup vs baseline: 1.0821x; 1.0087x over previous
.LBB0_558:
	v_readlane_b32 s1, v236, 50
	s_cmp_eq_u32 s0, s1
	s_mov_b64 s[0:1], -1
	s_cbranch_scc1 .LBB0_570
	s_mov_b64 s[0:1], 0
	s_branch .LBB0_570
	v_mov_b32 v0, v214
	v_mov_b32 v1, v214
	v_readlane_b32 s0, v236, 34
	v_ashrrev_i32_e32 v1, 6, v1
	s_nop 0
	v_add_u32_e32 v16, s0, v1
	v_cmp_gt_i32_e32 vcc, s3, v16
	s_and_saveexec_b64 s[0:1], vcc
	s_cbranch_execz .LBB0_564
	v_ashrrev_i32_e32 v17, 31, v16
	v_and_b32_e32 v2, 63, v0
	v_lshlrev_b64 v[0:1], 10, v[16:17]
	v_lshl_or_b32 v0, v2, 4, v0
	v_lshl_add_u64 v[20:21], s[6:7], 0, v[0:1]
	v_lshlrev_b64 v[0:1], 12, v[16:17]
	v_lshl_or_b32 v0, v2, 6, v0
	v_cmp_eq_u32_e64 s[40:41], 0, v2
	v_lshl_add_u64 v[18:19], v[16:17], 2, s[18:19]
	v_lshl_add_u64 v[22:23], s[14:15], 0, v[0:1]
	s_mov_b64 s[34:35], 0
	s_branch .LBB0_562

.LBB0_629:
	s_or_b64 exec, exec, s[10:11]
	s_add_u32 s22, s94, 0x188e8000
	s_addc_u32 s23, s95, 0
	s_add_u32 s24, s94, 0x1a8e8000
	s_addc_u32 s25, s95, 0
	v_and_b32_e32 v219, 63, v214
	v_lshlrev_b32_e32 v196, 6, v219
	v_lshlrev_b32_e32 v197, 4, v219
	v_lshlrev_b32_e32 v198, 3, v219
	v_lshrrev_b32_e32 v219, 6, v214
	v_mov_b32_e32 v199, 0
	v_readfirstlane_b32 s46, v219
	v_mov_b32_e32 v200, 0x43600000
	v_mov_b32_e32 v201, 0x3b924925
	v_mov_b32_e32 v202, 0x40c00000
	v_mov_b32_e32 v203, 0x3e2aaaab
	s_lshl_b32 s31, s70, 2
	s_add_u32 s31, s31, s46
	s_lshl_b32 s32, s2, 2
	v_readlane_b32 s34, v238, 28
	v_readlane_b32 s35, v238, 29
	v_readlane_b32 s36, v238, 30
	v_readlane_b32 s37, v238, 31
	s_mov_b32 s38, s31
	s_mov_b32 s33, 0
	s_cmpk_lt_i32 s70, 0x1000
	s_waitcnt lgkmcnt(0)
	s_barrier
	v_mov_b32 v0, v214
	v_mov_b32 v1, v214
	s_cbranch_scc0 .LBB0_632
	v_ashrrev_i32_e32 v1, 1, v1
	s_movk_i32 s0, 0xffe0
	v_bfi_b32 v2, s0, v1, v0
	s_movk_i32 s0, 0x210
	v_ashrrev_i32_e32 v3, 31, v2
	v_bfe_u32 v0, v0, 5, 1
	v_mul_lo_u32 v102, v2, s0
	v_lshlrev_b64 v[96:97], 8, v[2:3]
	s_add_u32 s3, s94, 0x1e00000
	v_lshlrev_b32_e32 v103, 6, v0
	v_lshl_add_u32 v104, v0, 8, v102
	v_cmp_eq_u32_e32 vcc, 0, v0
	v_lshl_or_b32 v96, v0, 3, v96
	v_and_b32_e32 v0, 64, v215
	s_addc_u32 s14, s95, 0
	v_or_b32_e32 v105, 1, v103
	v_or_b32_e32 v106, 2, v103
	v_or_b32_e32 v107, 3, v103
	v_or_b32_e32 v108, 4, v103
	v_or_b32_e32 v109, 5, v103
	v_or_b32_e32 v110, 6, v103
	v_or_b32_e32 v111, 7, v103
	v_or_b32_e32 v112, 8, v103
	v_or_b32_e32 v113, 9, v103
	v_or_b32_e32 v114, 10, v103
	v_or_b32_e32 v115, 11, v103
	v_or_b32_e32 v116, 12, v103
	v_or_b32_e32 v117, 13, v103
	v_or_b32_e32 v118, 14, v103
	v_or_b32_e32 v119, 15, v103
	v_mov_b32_e32 v99, 0
	s_movk_i32 s15, 0x90
	s_movk_i32 s16, 0x7f
	v_xor_b32_e32 v120, 32, v215
	v_add_u32_e32 v121, 64, v0
	s_mov_b32 s17, s70
	s_movk_i32 s28, 0x48
.LBB0_631:
	s_mov_b64 s[50:51], vcc
	s_cmp_eq_u32 s33, 0
	s_cbranch_scc1 .Lq_nofin
	s_waitcnt vmcnt(3)
	v_mov_b32_e32 v204, v199
	v_mov_b32_e32 v205, v199
	v_mov_b32_e32 v206, v199
	v_mov_b32_e32 v207, v199
	v_max_f32_e64 v208, |v179|, |v179|
	v_max_f32_e64 v209, |v178|, |v178|
	v_max_f32_e64 v210, |v175|, |v175|
	v_max_f32_e64 v211, |v174|, |v174|
	v_max_f32_e64 v212, |v171|, |v171|
	v_max_f32_e64 v213, |v170|, |v170|
	v_max_f32_e64 v216, |v167|, |v167|
	v_max_f32_e64 v217, |v166|, |v166|
	v_max_f32_e32 v208, v209, v208
	v_max_f32_e32 v209, v211, v210
	v_max_f32_e32 v210, v213, v212
	v_max_f32_e32 v211, v217, v216
	v_max3_f32 v208, |v176|, |v177|, v208
	v_max3_f32 v209, |v172|, |v173|, v209
	v_max3_f32 v210, |v168|, |v169|, v210
	v_max3_f32 v211, |v164|, |v165|, v211
	v_max3_f32 v208, v208, 0, v209
	v_max3_f32 v208, v208, v210, v211
	v_mov_b32_e32 v209, v208
	s_nop 1
	v_mov_b32_dpp v209, v209 quad_perm:[1,0,3,2] row_mask:0xf bank_mask:0xf
	v_max_f32_e32 v209, v209, v209
	v_max_f32_e32 v208, v208, v209
	v_mov_b32_e32 v209, v208
	s_nop 1
	v_mov_b32_dpp v209, v209 quad_perm:[2,3,0,1] row_mask:0xf bank_mask:0xf
	v_max_f32_e32 v209, v209, v209
	v_max_f32_e32 v208, v208, v209
	v_mov_b32_e32 v209, v208
	s_nop 1
	v_mov_b32_dpp v209, v209 row_half_mirror row_mask:0xf bank_mask:0xf
	v_max_f32_e32 v209, v209, v209
	v_max_f32_e32 v208, v208, v209
	v_mov_b32_e32 v209, v208
	s_nop 1
	v_mov_b32_dpp v209, v209 row_mirror row_mask:0xf bank_mask:0xf
	v_max_f32_e32 v209, v209, v209
	v_max_f32_e32 v208, v208, v209
	v_mov_b32_e32 v209, v208
	s_nop 1
	v_mov_b32_dpp v209, v209 row_bcast:15 row_mask:0xa bank_mask:0xf
	v_max_f32_e32 v209, v209, v209
	v_max_f32_e32 v208, v208, v209
	v_mov_b32_e32 v209, v208
	s_nop 1
	v_mov_b32_dpp v209, v209 row_bcast:31 row_mask:0xc bank_mask:0xf
	v_max_f32_e32 v209, v209, v209
	v_max_f32_e32 v208, v208, v209
	s_nop 0
	v_readlane_b32 s40, v208, 63
	s_nop 1
	v_div_scale_f32 v208, s[42:43], s40, s40, v200
	v_rcp_f32_e32 v209, v208
	v_mov_b32_e32 v210, s40
	s_mov_b32 s42, 0x43600000
	v_div_scale_f32 v210, vcc, s42, v210, s42
	v_fma_f32 v211, -v208, v209, 1.0
	v_fmac_f32_e32 v209, v211, v209
	v_mul_f32_e32 v211, v210, v209
	v_fma_f32 v212, -v208, v211, v210
	v_fmac_f32_e32 v211, v212, v209
	v_fma_f32 v208, -v208, v211, v210
	v_div_fmas_f32 v208, v208, v209, v211
	v_div_fixup_f32 v208, v208, s40, v200
	v_cmp_gt_f32_e64 vcc, s40, 0
	s_nop 1
	v_cndmask_b32_e32 v208, 1.0, v208, vcc
	v_mul_f32_e32 v176, v176, v208
	v_mul_f32_e32 v177, v177, v208
	v_mul_f32_e32 v172, v172, v208
	v_mul_f32_e32 v173, v173, v208
	v_mul_f32_e32 v168, v168, v208
	v_mul_f32_e32 v169, v169, v208
	v_mul_f32_e32 v164, v164, v208
	v_mul_f32_e32 v165, v165, v208
	v_cvt_pk_fp8_f32 v204, v176, v177
	v_cvt_pk_fp8_f32 v205, v172, v173
	v_cvt_pk_fp8_f32 v206, v168, v169
	v_cvt_pk_fp8_f32 v207, v164, v165
	v_mul_f32_e32 v178, v178, v208
	v_mul_f32_e32 v179, v179, v208
	v_mul_f32_e32 v174, v174, v208
	v_mul_f32_e32 v175, v175, v208
	v_mul_f32_e32 v170, v170, v208
	v_mul_f32_e32 v171, v171, v208
	v_mul_f32_e32 v166, v166, v208
	v_mul_f32_e32 v167, v167, v208
	v_cvt_pk_fp8_f32 v204, v178, v179 op_sel:[0,0,1]
	v_cvt_pk_fp8_f32 v205, v174, v175 op_sel:[0,0,1]
	v_cvt_pk_fp8_f32 v206, v170, v171 op_sel:[0,0,1]
	v_cvt_pk_fp8_f32 v207, v166, v167 op_sel:[0,0,1]
	s_lshl_b32 s46, s39, 10
	s_add_u32 s48, s94, 0x28c0000
	s_addc_u32 s49, s95, 0
	s_add_u32 s48, s48, s46
	s_addc_u32 s49, s49, 0
	global_store_dwordx4 v197, v[204:207], s[48:49]
	v_mul_f32_e32 v218, s40, v201
	v_cndmask_b32_e32 v218, 1.0, v218, vcc
	s_lshl_b32 s46, s39, 2
	s_add_u32 s48, s94, 0x38c0000
	s_addc_u32 s49, s95, 0
	s_add_u32 s48, s48, s46
	s_addc_u32 s49, s49, 0
	s_mov_b64 s[44:45], exec
	s_mov_b64 exec, 1
	global_store_dword v199, v218, s[48:49]
	s_mov_b64 exec, s[44:45]
	v_mov_b32_e32 v204, v199
	v_mov_b32_e32 v205, v199
	v_max_f32_e64 v208, |v195|, |v195|
	v_max_f32_e64 v206, |v194|, |v194|
	v_max_f32_e64 v207, |v191|, |v191|
	v_max_f32_e64 v209, |v190|, |v190|
	v_max_f32_e64 v210, |v187|, |v187|
	v_max_f32_e64 v211, |v186|, |v186|
	v_max_f32_e64 v212, |v183|, |v183|
	v_max_f32_e64 v213, |v182|, |v182|
	v_max_f32_e32 v208, v206, v208
	v_max_f32_e32 v206, v209, v207
	v_max_f32_e32 v207, v211, v210
	v_max_f32_e32 v209, v213, v212
	v_max3_f32 v208, |v192|, |v193|, v208
	v_max3_f32 v206, |v188|, |v189|, v206
	v_max3_f32 v207, |v184|, |v185|, v207
	v_max3_f32 v209, |v180|, |v181|, v209
	v_max3_f32 v208, v208, 0, v206
	v_max3_f32 v208, v208, v207, v209
	v_mov_b32_e32 v206, v208
	s_nop 1
	v_mov_b32_dpp v206, v206 quad_perm:[1,0,3,2] row_mask:0xf bank_mask:0xf
	v_max_f32_e32 v206, v206, v206
	v_max_f32_e32 v208, v208, v206
	v_mov_b32_e32 v206, v208
	s_nop 1
	v_mov_b32_dpp v206, v206 quad_perm:[2,3,0,1] row_mask:0xf bank_mask:0xf
	v_max_f32_e32 v206, v206, v206
	v_max_f32_e32 v208, v208, v206
	v_mov_b32_e32 v206, v208
	s_nop 1
	v_mov_b32_dpp v206, v206 row_half_mirror row_mask:0xf bank_mask:0xf
	v_max_f32_e32 v206, v206, v206
	v_max_f32_e32 v208, v208, v206
	v_mov_b32_e32 v206, v208
	s_nop 1
	v_mov_b32_dpp v206, v206 row_mirror row_mask:0xf bank_mask:0xf
	v_max_f32_e32 v206, v206, v206
	v_max_f32_e32 v208, v208, v206
	v_mov_b32_e32 v206, v208
	s_nop 1
	v_mov_b32_dpp v206, v206 row_bcast:15 row_mask:0xa bank_mask:0xf
	v_max_f32_e32 v206, v206, v206
	v_max_f32_e32 v208, v208, v206
	v_mov_b32_e32 v206, v208
	s_nop 1
	v_mov_b32_dpp v206, v206 row_bcast:31 row_mask:0xc bank_mask:0xf
	v_max_f32_e32 v206, v206, v206
	v_max_f32_e32 v208, v208, v206
	s_nop 0
	v_readlane_b32 s40, v208, 63
	s_nop 1
	v_div_scale_f32 v208, s[42:43], s40, s40, v202
	v_rcp_f32_e32 v206, v208
	v_mov_b32_e32 v207, s40
	s_mov_b32 s42, 0x40c00000
	v_div_scale_f32 v207, vcc, s42, v207, s42
	v_fma_f32 v209, -v208, v206, 1.0
	v_fmac_f32_e32 v206, v209, v206
	v_mul_f32_e32 v209, v207, v206
	v_fma_f32 v210, -v208, v209, v207
	v_fmac_f32_e32 v209, v210, v206
	v_fma_f32 v208, -v208, v209, v207
	v_div_fmas_f32 v208, v208, v206, v209
	v_div_fixup_f32 v208, v208, s40, v202
	v_cmp_gt_f32_e64 vcc, s40, 0
	s_nop 1
	v_cndmask_b32_e32 v208, 1.0, v208, vcc
	v_mul_f32_e32 v192, v192, v208
	v_mul_f32_e32 v193, v193, v208
	v_mul_f32_e32 v184, v184, v208
	v_mul_f32_e32 v185, v185, v208
	v_mul_f32_e32 v194, v194, v208
	v_mul_f32_e32 v195, v195, v208
	v_mul_f32_e32 v186, v186, v208
	v_mul_f32_e32 v187, v187, v208
	v_cvt_scalef32_pk_fp4_f32 v204, v192, v193, 1.0
	v_cvt_scalef32_pk_fp4_f32 v205, v184, v185, 1.0
	v_mul_f32_e32 v188, v188, v208
	v_mul_f32_e32 v189, v189, v208
	v_mul_f32_e32 v180, v180, v208
	v_mul_f32_e32 v181, v181, v208
	v_cvt_scalef32_pk_fp4_f32 v204, v194, v195, 1.0 op_sel:[0,0,1,0]
	v_cvt_scalef32_pk_fp4_f32 v205, v186, v187, 1.0 op_sel:[0,0,1,0]
	v_mul_f32_e32 v190, v190, v208
	v_mul_f32_e32 v191, v191, v208
	v_mul_f32_e32 v182, v182, v208
	v_mul_f32_e32 v183, v183, v208
	v_cvt_scalef32_pk_fp4_f32 v204, v188, v189, 1.0 op_sel:[0,0,0,1]
	v_cvt_scalef32_pk_fp4_f32 v205, v180, v181, 1.0 op_sel:[0,0,0,1]
	v_cvt_scalef32_pk_fp4_f32 v204, v190, v191, 1.0 op_sel:[0,0,1,1]
	v_cvt_scalef32_pk_fp4_f32 v205, v182, v183, 1.0 op_sel:[0,0,1,1]
	s_lshl_b32 s46, s39, 9
	s_add_u32 s48, s94, 0x38d0000
	s_addc_u32 s49, s95, 0
	s_add_u32 s48, s48, s46
	s_addc_u32 s49, s49, 0
	global_store_dwordx2 v198, v[204:205], s[48:49]
	v_mul_f32_e32 v218, s40, v203
	v_cndmask_b32_e32 v218, 1.0, v218, vcc
	s_lshl_b32 s46, s39, 2
	s_add_u32 s48, s94, 0x48d0000
	s_addc_u32 s49, s95, 0
	s_add_u32 s48, s48, s46
	s_addc_u32 s49, s49, 0
	s_mov_b64 s[44:45], exec
	s_mov_b64 exec, 1
	global_store_dword v199, v218, s[48:49]
	s_mov_b64 exec, s[44:45]
.Lq_nofin:
	s_mov_b32 s33, 0
	s_cmp_ge_u32 s38, 0x4000
	s_cbranch_scc1 .Lq_noissue
	s_lshl_b32 s46, s38, 12
	s_add_u32 s48, s34, s46
	s_addc_u32 s49, s35, 0
	global_load_dwordx4 v[176:179], v196, s[48:49]
	global_load_dwordx4 v[172:175], v196, s[48:49] offset:16
	global_load_dwordx4 v[168:171], v196, s[48:49] offset:32
	global_load_dwordx4 v[164:167], v196, s[48:49] offset:48
	s_add_u32 s48, s36, s46
	s_addc_u32 s49, s37, 0
	global_load_dwordx4 v[192:195], v196, s[48:49]
	global_load_dwordx4 v[188:191], v196, s[48:49] offset:16
	global_load_dwordx4 v[184:187], v196, s[48:49] offset:32
	global_load_dwordx4 v[180:183], v196, s[48:49] offset:48
	s_mov_b32 s39, s38
	s_add_u32 s38, s38, s32
	s_mov_b32 s33, 1
.Lq_noissue:
	s_mov_b64 vcc, s[50:51]
	s_ashr_i32 s0, s17, 31
	s_lshr_b32 s0, s0, 24
	s_add_i32 s0, s17, s0
	s_ashr_i32 s10, s0, 8
	s_and_b32 s0, s0, 0xffffff00
	s_sub_i32 s12, s17, s0
	s_ashr_i32 s13, s12, 31
	s_lshl_b64 s[0:1], s[12:13], 19
	s_add_u32 s11, s78, s0
	s_addc_u32 s27, s79, s1
	s_lshl_b32 s0, s10, 7
	s_ashr_i32 s1, s0, 31
	s_lshl_b64 s[0:1], s[0:1], 1
	s_add_u32 s26, s11, s0
	s_addc_u32 s27, s27, s1
	s_ashr_i32 s11, s10, 31
	s_lshl_b64 s[0:1], s[10:11], 15
	v_mov_b32 v48, v214
	s_add_u32 s0, s3, s0
	v_lshlrev_b32_e32 v0, 3, v48
	v_ashrrev_i32_e32 v1, 3, v48
	v_and_b32_e32 v49, 56, v0
	s_addc_u32 s1, s14, s1
	v_lshl_or_b32 v0, v1, 7, v49
	v_mul_lo_u32 v50, v1, s28
	v_lshl_or_b32 v98, v1, 11, v49
	v_mov_b32_e32 v1, v99
	v_lshl_add_u64 v[32:33], v[98:99], 1, s[26:27]
	v_lshl_add_u64 v[34:35], v[0:1], 1, s[0:1]
	s_mov_b32 s0, 0x20000
	v_add_co_u32_e64 v36, s[0:1], s0, v32
	global_load_dwordx4 v[0:3], v[32:33], off
	global_load_dwordx4 v[4:7], v[34:35], off
	v_addc_co_u32_e64 v37, s[0:1], 0, v33, s[0:1]
	s_movk_i32 s0, 0x2000
	s_nop 0
	v_add_co_u32_e64 v38, s[0:1], s0, v34
	global_load_dwordx4 v[8:11], v[36:37], off
	s_nop 0
	v_addc_co_u32_e64 v39, s[0:1], 0, v35, s[0:1]
	s_mov_b32 s0, 0x40000
	s_nop 0
	v_add_co_u32_e64 v40, s[0:1], s0, v32
	global_load_dwordx4 v[12:15], v[38:39], off
	s_nop 0
	v_addc_co_u32_e64 v41, s[0:1], 0, v33, s[0:1]
	s_movk_i32 s0, 0x4000
	s_nop 0
	v_add_co_u32_e64 v42, s[0:1], s0, v34
	global_load_dwordx4 v[16:19], v[40:41], off
	s_nop 0
	v_addc_co_u32_e64 v43, s[0:1], 0, v35, s[0:1]
	s_mov_b32 s0, 0x60000
	s_nop 0
	v_add_co_u32_e64 v44, s[0:1], s0, v32
	global_load_dwordx4 v[20:23], v[42:43], off
	s_nop 0
	v_addc_co_u32_e64 v45, s[0:1], 0, v33, s[0:1]
	s_movk_i32 s0, 0x6000
	global_load_dwordx4 v[28:31], v[44:45], off
	v_add_co_u32_e64 v46, s[0:1], s0, v34
	v_add_lshl_u32 v98, v50, v49, 1
	s_nop 0
	v_addc_co_u32_e64 v47, s[0:1], 0, v35, s[0:1]
	global_load_dwordx4 v[24:27], v[46:47], off
	global_load_dwordx4 v[80:83], v[32:33], off offset:128
	global_load_dwordx4 v[84:87], v[34:35], off offset:128
	global_load_dwordx4 v[88:91], v[36:37], off offset:128
	global_load_dwordx4 v[92:95], v[38:39], off offset:128
	global_load_dwordx4 v[64:67], v[40:41], off offset:128
	global_load_dwordx4 v[68:71], v[42:43], off offset:128
	global_load_dwordx4 v[72:75], v[44:45], off offset:128
	global_load_dwordx4 v[76:79], v[46:47], off offset:128
	v_and_b32_e32 v32, 31, v48
	v_lshrrev_b32_e32 v34, 1, v48
	s_mov_b32 s0, 0xfffffc0
	v_and_b32_e32 v33, 0x5f, v48
	v_and_or_b32 v35, v34, s0, v32
	v_and_b32_e32 v32, 16, v34
	s_waitcnt vmcnt(21)
	v_mad_u32_u24 v138, v33, s15, v32
	s_barrier
	v_mad_u64_u32 v[100:101], s[0:1], v35, s15, v[32:33]
	v_add_u32_e32 v101, 0xd800, v98
	s_lshl_b64 s[10:11], s[10:11], 4
	s_waitcnt vmcnt(15)
	ds_write_b128 v98, v[0:3]
	s_waitcnt vmcnt(14)
	ds_write_b128 v98, v[4:7] offset:18432
	s_waitcnt vmcnt(13)
	ds_write_b128 v98, v[8:11] offset:4608
	s_waitcnt vmcnt(12)
	ds_write_b128 v98, v[12:15] offset:23040
	s_waitcnt vmcnt(11)
	ds_write_b128 v98, v[16:19] offset:9216
	s_waitcnt vmcnt(10)
	ds_write_b128 v98, v[20:23] offset:27648
	s_waitcnt vmcnt(9)
	ds_write_b128 v98, v[28:31] offset:13824
	s_waitcnt vmcnt(8)
	ds_write_b128 v98, v[24:27] offset:32256
	s_waitcnt lgkmcnt(0)
	s_barrier
	ds_read_b128 v[16:19], v138 offset:4608
	ds_read_b128 v[20:23], v100 offset:23040
	ds_read_b128 v[0:3], v138
	ds_read_b128 v[122:125], v138 offset:32
	ds_read_b128 v[4:7], v100 offset:18432
	ds_read_b128 v[126:129], v100 offset:18464
	s_waitcnt lgkmcnt(1)
	v_mfma_f32_32x32x16_bf16 v[32:47], v[0:3], v[4:7], 0
	ds_read_b128 v[130:133], v138 offset:4640
	ds_read_b128 v[134:137], v100 offset:23072
	v_mfma_f32_32x32x16_bf16 v[48:63], v[0:3], v[20:23], 0
	v_mfma_f32_32x32x16_bf16 v[0:15], v[16:19], v[4:7], 0
	v_mfma_f32_32x32x16_bf16 v[16:31], v[16:19], v[20:23], 0
	s_waitcnt lgkmcnt(2)
	v_mfma_f32_32x32x16_bf16 v[32:47], v[122:125], v[126:129], v[32:47]
	s_waitcnt lgkmcnt(0)
	v_mfma_f32_32x32x16_bf16 v[48:63], v[122:125], v[134:137], v[48:63]
	v_mfma_f32_32x32x16_bf16 v[0:15], v[130:133], v[126:129], v[0:15]
	v_mfma_f32_32x32x16_bf16 v[16:31], v[130:133], v[134:137], v[16:31]
	ds_read_b128 v[122:125], v138 offset:64
	ds_read_b128 v[126:129], v138 offset:4672
	ds_read_b128 v[130:133], v100 offset:18496
	ds_read_b128 v[134:137], v100 offset:23104
	s_waitcnt lgkmcnt(1)
	v_mfma_f32_32x32x16_bf16 v[32:47], v[122:125], v[130:133], v[32:47]
	s_waitcnt lgkmcnt(0)
	v_mfma_f32_32x32x16_bf16 v[48:63], v[122:125], v[134:137], v[48:63]
	v_mfma_f32_32x32x16_bf16 v[0:15], v[126:129], v[130:133], v[0:15]
	v_mfma_f32_32x32x16_bf16 v[16:31], v[126:129], v[134:137], v[16:31]
	ds_read_b128 v[122:125], v138 offset:96
	ds_read_b128 v[126:129], v138 offset:4704
	ds_read_b128 v[130:133], v100 offset:18528
	ds_read_b128 v[134:137], v100 offset:23136
	s_waitcnt vmcnt(7)
	ds_write_b128 v98, v[80:83] offset:36864
	s_waitcnt vmcnt(6)
	ds_write_b128 v98, v[84:87] offset:55296
	s_waitcnt vmcnt(5)
	ds_write_b128 v98, v[88:91] offset:41472
	s_waitcnt vmcnt(4)
	ds_write_b128 v98, v[92:95] offset:59904
	s_waitcnt vmcnt(3)
	ds_write_b128 v98, v[64:67] offset:46080
	s_waitcnt vmcnt(2)
	ds_write_b128 v98, v[68:71] offset:64512
	s_waitcnt vmcnt(1)
	ds_write_b128 v98, v[72:75] offset:50688
	s_waitcnt vmcnt(0)
	ds_write_b128 v101, v[76:79] offset:13824
	s_waitcnt lgkmcnt(0)
	s_barrier
	ds_read_b128 v[64:67], v138 offset:41472
	ds_read_b128 v[68:71], v100 offset:59904
	ds_read_b128 v[72:75], v138 offset:36864
	ds_read_b128 v[76:79], v138 offset:36896
	ds_read_b128 v[80:83], v100 offset:55296
	ds_read_b128 v[84:87], v100 offset:55328
	v_mfma_f32_32x32x16_bf16 v[32:47], v[122:125], v[130:133], v[32:47]
	v_mfma_f32_32x32x16_bf16 v[48:63], v[122:125], v[134:137], v[48:63]
	v_mfma_f32_32x32x16_bf16 v[0:15], v[126:129], v[130:133], v[0:15]
	v_mfma_f32_32x32x16_bf16 v[16:31], v[126:129], v[134:137], v[16:31]
	s_waitcnt lgkmcnt(1)
	v_mfma_f32_32x32x16_bf16 v[32:47], v[72:75], v[80:83], v[32:47]
	v_mfma_f32_32x32x16_bf16 v[48:63], v[72:75], v[68:71], v[48:63]
	v_mfma_f32_32x32x16_bf16 v[0:15], v[64:67], v[80:83], v[0:15]
	v_mfma_f32_32x32x16_bf16 v[16:31], v[64:67], v[68:71], v[16:31]
	ds_read_b128 v[64:67], v138 offset:41504
	ds_read_b128 v[68:71], v100 offset:59936
	s_waitcnt lgkmcnt(2)
	v_mfma_f32_32x32x16_bf16 v[32:47], v[76:79], v[84:87], v[32:47]
	s_waitcnt lgkmcnt(0)
	v_mfma_f32_32x32x16_bf16 v[48:63], v[76:79], v[68:71], v[48:63]
	v_mfma_f32_32x32x16_bf16 v[0:15], v[64:67], v[84:87], v[0:15]
	v_mfma_f32_32x32x16_bf16 v[16:31], v[64:67], v[68:71], v[16:31]
	ds_read_b128 v[64:67], v138 offset:36928
	ds_read_b128 v[68:71], v138 offset:41536
	ds_read_b128 v[72:75], v100 offset:55360
	ds_read_b128 v[76:79], v100 offset:59968
	s_waitcnt lgkmcnt(1)
	v_mfma_f32_32x32x16_bf16 v[32:47], v[64:67], v[72:75], v[32:47]
	s_waitcnt lgkmcnt(0)
	v_mfma_f32_32x32x16_bf16 v[48:63], v[64:67], v[76:79], v[48:63]
	v_mfma_f32_32x32x16_bf16 v[0:15], v[68:71], v[72:75], v[0:15]
	v_mfma_f32_32x32x16_bf16 v[16:31], v[68:71], v[76:79], v[16:31]
	ds_read_b128 v[64:67], v138 offset:36960
	ds_read_b128 v[68:71], v138 offset:41568
	ds_read_b128 v[72:75], v100 offset:55392
	ds_read_b128 v[76:79], v100 offset:60000
	s_waitcnt lgkmcnt(1)
	v_mfma_f32_32x32x16_bf16 v[32:47], v[64:67], v[72:75], v[32:47]
	s_waitcnt lgkmcnt(0)
	v_mfma_f32_32x32x16_bf16 v[48:63], v[64:67], v[76:79], v[48:63]
	v_mov_b32 v64, v214
	v_mov_b32 v65, v214
	s_nop 0
	v_lshrrev_b32_e32 v66, 3, v64
	v_and_b32_e32 v66, 4, v66
	v_and_or_b32 v66, v65, 64, v66
	v_lshlrev_b32_e32 v65, 1, v65
	v_and_b32_e32 v64, 31, v64
	v_mul_u32_u24_e32 v66, 0x210, v66
	v_and_b32_e32 v65, 0xffffff00, v65
	v_lshlrev_b32_e32 v64, 2, v64
	v_add3_u32 v64, v66, v65, v64
	s_barrier
	s_nop 0
	ds_write2_b32 v64, v32, v48 offset1:32
	ds_write2_b32 v64, v33, v49 offset0:132 offset1:164
	v_add_u32_e32 v32, 0x400, v64
	ds_write2_b32 v32, v34, v50 offset0:8 offset1:40
	ds_write2_b32 v32, v35, v51 offset0:140 offset1:172
	v_add_u32_e32 v32, 0x1000, v64
	v_mfma_f32_32x32x16_bf16 v[0:15], v[68:71], v[72:75], v[0:15]
	ds_write2_b32 v32, v36, v52 offset0:32 offset1:64
	ds_write2_b32 v32, v37, v53 offset0:164 offset1:196
	v_add_u32_e32 v32, 0x1400, v64
	ds_write2_b32 v32, v38, v54 offset0:40 offset1:72
	ds_write2_b32 v32, v39, v55 offset0:172 offset1:204
	v_add_u32_e32 v32, 0x2000, v64
	ds_write2_b32 v32, v40, v56 offset0:64 offset1:96
	ds_write2_b32 v32, v41, v57 offset0:196 offset1:228
	v_add_u32_e32 v32, 0x2400, v64
	ds_write2_b32 v32, v42, v58 offset0:72 offset1:104
	ds_write2_b32 v32, v43, v59 offset0:204 offset1:236
	v_mfma_f32_32x32x16_bf16 v[16:31], v[68:71], v[76:79], v[16:31]
	v_add_u32_e32 v32, 0x3000, v64
	ds_write2_b32 v32, v44, v60 offset0:96 offset1:128
	v_add_u32_e32 v32, 0x3200, v64
	ds_write2_b32 v32, v45, v61 offset0:100 offset1:132
	v_add_u32_e32 v32, 0x3400, v64
	ds_write2_b32 v32, v46, v62 offset0:104 offset1:136
	v_add_u32_e32 v32, 0x3600, v64
	ds_write2_b32 v32, v47, v63 offset0:108 offset1:140
	v_add_u32_e32 v32, 0x4000, v64
	s_nop 2
	ds_write2_b32 v32, v0, v16 offset0:128 offset1:160
	v_add_u32_e32 v0, 0x4400, v64
	ds_write2_b32 v0, v1, v17 offset0:4 offset1:36
	ds_write2_b32 v0, v2, v18 offset0:136 offset1:168
	v_add_u32_e32 v0, 0x4800, v64
	ds_write2_b32 v0, v3, v19 offset0:12 offset1:44
	v_add_u32_e32 v0, 0x5000, v64
	ds_write2_b32 v0, v4, v20 offset0:160 offset1:192
	v_add_u32_e32 v0, 0x5400, v64
	ds_write2_b32 v0, v5, v21 offset0:36 offset1:68
	ds_write2_b32 v0, v6, v22 offset0:168 offset1:200
	v_add_u32_e32 v0, 0x5800, v64
	ds_write2_b32 v0, v7, v23 offset0:44 offset1:76
	v_add_u32_e32 v0, 0x6000, v64
	ds_write2_b32 v0, v8, v24 offset0:192 offset1:224
	v_add_u32_e32 v0, 0x6400, v64
	ds_write2_b32 v0, v9, v25 offset0:68 offset1:100
	ds_write2_b32 v0, v10, v26 offset0:200 offset1:232
	v_add_u32_e32 v0, 0x6800, v64
	ds_write2_b32 v0, v11, v27 offset0:76 offset1:108
	v_add_u32_e32 v0, 0x7200, v64
	ds_write2_b32 v0, v12, v28 offset0:96 offset1:128
	v_add_u32_e32 v0, 0x7400, v64
	ds_write2_b32 v0, v13, v29 offset0:100 offset1:132
	v_add_u32_e32 v0, 0x7600, v64
	ds_write2_b32 v0, v14, v30 offset0:104 offset1:136
	v_add_u32_e32 v0, 0x7800, v64
	ds_write2_b32 v0, v15, v31 offset0:108 offset1:140
	s_waitcnt lgkmcnt(0)
	s_barrier
	ds_read_b128 v[8:11], v104 offset:64
	ds_read_b128 v[16:19], v104 offset:128
	ds_read_b128 v[26:29], v104 offset:192
	ds_read_b128 v[30:33], v104
	ds_read_b128 v[34:37], v104 offset:16
	ds_read_b128 v[4:7], v104 offset:32
	ds_read_b128 v[0:3], v104 offset:48
	s_waitcnt lgkmcnt(3)
	v_not_b32_e32 v12, v30
	v_or_b32_e32 v13, 0x80000000, v30
	v_cmp_gt_i32_e64 s[0:1], 0, v30
	s_waitcnt lgkmcnt(2)
	v_or_b32_e32 v15, 0x80000000, v35
	v_or_b32_e32 v25, 0x80000000, v37
	v_cndmask_b32_e64 v12, v13, v12, s[0:1]
	v_and_b32_e32 v12, 0xffffff80, v12
	v_sub_u32_e32 v12, v12, v103
	v_add_u32_e32 v46, 0x7f, v12
	v_not_b32_e32 v12, v8
	v_or_b32_e32 v13, 0x80000000, v8
	v_cmp_gt_i32_e64 s[0:1], 0, v8
	s_waitcnt lgkmcnt(0)
	v_not_b32_e32 v64, v0
	v_or_b32_e32 v65, 0x80000000, v0
	v_cndmask_b32_e64 v8, v13, v12, s[0:1]
	v_and_b32_e32 v8, 0xffffff80, v8
	v_sub_u32_e32 v8, v8, v103
	v_add_u32_e32 v22, 0x6f, v8
	v_not_b32_e32 v8, v16
	v_or_b32_e32 v12, 0x80000000, v16
	v_cmp_gt_i32_e64 s[0:1], 0, v16
	v_or_b32_e32 v13, 0x80000000, v31
	s_nop 0
	v_cndmask_b32_e64 v8, v12, v8, s[0:1]
	v_and_b32_e32 v8, 0xffffff80, v8
	v_sub_u32_e32 v8, v8, v103
	v_add_u32_e32 v14, 0x5f, v8
	v_not_b32_e32 v8, v26
	v_or_b32_e32 v12, 0x80000000, v26
	v_cmp_gt_i32_e64 s[0:1], 0, v26
	s_nop 1
	v_cndmask_b32_e64 v8, v12, v8, s[0:1]
	v_not_b32_e32 v12, v31
	v_cmp_gt_i32_e64 s[0:1], 0, v31
	v_and_b32_e32 v8, 0xffffff80, v8
	v_sub_u32_e32 v8, v8, v103
	v_cndmask_b32_e64 v12, v13, v12, s[0:1]
	v_and_b32_e32 v12, 0xffffff80, v12
	v_sub_u32_e32 v12, v12, v105
	v_add_u32_e32 v47, 0x7f, v12
	v_not_b32_e32 v12, v9
	v_or_b32_e32 v13, 0x80000000, v9
	v_cmp_gt_i32_e64 s[0:1], 0, v9
	v_add_u32_e32 v8, 0x4f, v8
	s_nop 0
	v_cndmask_b32_e64 v9, v13, v12, s[0:1]
	v_and_b32_e32 v9, 0xffffff80, v9
	v_sub_u32_e32 v9, v9, v105
	v_add_u32_e32 v24, 0x6f, v9
	v_not_b32_e32 v9, v17
	v_or_b32_e32 v12, 0x80000000, v17
	v_cmp_gt_i32_e64 s[0:1], 0, v17
	v_or_b32_e32 v13, 0x80000000, v32
	v_or_b32_e32 v17, 0x80000000, v36
	v_cndmask_b32_e64 v9, v12, v9, s[0:1]
	v_and_b32_e32 v9, 0xffffff80, v9
	v_sub_u32_e32 v9, v9, v105
	v_add_u32_e32 v16, 0x5f, v9
	v_not_b32_e32 v9, v27
	v_or_b32_e32 v12, 0x80000000, v27
	v_cmp_gt_i32_e64 s[0:1], 0, v27
	v_max_u32_e32 v72, v22, v24
	v_min_u32_e32 v22, v22, v24
	v_cndmask_b32_e64 v9, v12, v9, s[0:1]
	v_not_b32_e32 v12, v32
	v_cmp_gt_i32_e64 s[0:1], 0, v32
	v_and_b32_e32 v9, 0xffffff80, v9
	v_sub_u32_e32 v9, v9, v105
	v_cndmask_b32_e64 v12, v13, v12, s[0:1]
	v_and_b32_e32 v12, 0xffffff80, v12
	v_sub_u32_e32 v12, v12, v106
	v_add_u32_e32 v48, 0x7f, v12
	v_not_b32_e32 v12, v10
	v_or_b32_e32 v13, 0x80000000, v10
	v_cmp_gt_i32_e64 s[0:1], 0, v10
	v_add_u32_e32 v9, 0x4f, v9
	v_max_u32_e32 v80, v14, v16
	v_cndmask_b32_e64 v10, v13, v12, s[0:1]
	v_and_b32_e32 v10, 0xffffff80, v10
	v_sub_u32_e32 v10, v10, v106
	v_add_u32_e32 v26, 0x6f, v10
	v_not_b32_e32 v10, v18
	v_or_b32_e32 v12, 0x80000000, v18
	v_cmp_gt_i32_e64 s[0:1], 0, v18
	v_or_b32_e32 v13, 0x80000000, v33
	v_min_u32_e32 v14, v14, v16
	v_cndmask_b32_e64 v10, v12, v10, s[0:1]
	v_and_b32_e32 v10, 0xffffff80, v10
	v_sub_u32_e32 v10, v10, v106
	v_add_u32_e32 v18, 0x5f, v10
	v_not_b32_e32 v10, v28
	v_or_b32_e32 v12, 0x80000000, v28
	v_cmp_gt_i32_e64 s[0:1], 0, v28
	v_max_u32_e32 v88, v8, v9
	v_min_u32_e32 v8, v8, v9
	v_cndmask_b32_e64 v10, v12, v10, s[0:1]
	v_not_b32_e32 v12, v33
	v_cmp_gt_i32_e64 s[0:1], 0, v33
	ds_read_b128 v[30:33], v104 offset:80
	ds_read_b128 v[38:41], v104 offset:144
	ds_read_b128 v[42:45], v104 offset:208
	v_cndmask_b32_e64 v12, v13, v12, s[0:1]
	v_and_b32_e32 v12, 0xffffff80, v12
	v_sub_u32_e32 v12, v12, v107
	v_add_u32_e32 v49, 0x7f, v12
	v_not_b32_e32 v12, v11
	v_or_b32_e32 v13, 0x80000000, v11
	v_cmp_gt_i32_e64 s[0:1], 0, v11
	s_waitcnt lgkmcnt(0)
	v_or_b32_e32 v27, 0x80000000, v45
	v_and_b32_e32 v10, 0xffffff80, v10
	v_cndmask_b32_e64 v11, v13, v12, s[0:1]
	v_and_b32_e32 v11, 0xffffff80, v11
	v_sub_u32_e32 v11, v11, v107
	v_add_u32_e32 v28, 0x6f, v11
	v_not_b32_e32 v11, v19
	v_or_b32_e32 v12, 0x80000000, v19
	v_cmp_gt_i32_e64 s[0:1], 0, v19
	v_or_b32_e32 v13, 0x80000000, v34
	v_sub_u32_e32 v10, v10, v106
	v_cndmask_b32_e64 v11, v12, v11, s[0:1]
	v_and_b32_e32 v11, 0xffffff80, v11
	v_sub_u32_e32 v11, v11, v107
	v_add_u32_e32 v19, 0x5f, v11
	v_not_b32_e32 v11, v29
	v_or_b32_e32 v12, 0x80000000, v29
	v_cmp_gt_i32_e64 s[0:1], 0, v29
	v_add_u32_e32 v10, 0x4f, v10
	v_max_u32_e32 v24, v28, v26
	v_cndmask_b32_e64 v11, v12, v11, s[0:1]
	v_not_b32_e32 v12, v34
	v_cmp_gt_i32_e64 s[0:1], 0, v34
	v_and_b32_e32 v11, 0xffffff80, v11
	v_sub_u32_e32 v11, v11, v107
	v_cndmask_b32_e64 v12, v13, v12, s[0:1]
	v_and_b32_e32 v12, 0xffffff80, v12
	v_sub_u32_e32 v12, v12, v108
	v_add_u32_e32 v29, 0x7f, v12
	v_not_b32_e32 v12, v30
	v_or_b32_e32 v13, 0x80000000, v30
	v_cmp_gt_i32_e64 s[0:1], 0, v30
	v_add_u32_e32 v11, 0x4f, v11
	v_min_u32_e32 v26, v28, v26
	v_cndmask_b32_e64 v12, v13, v12, s[0:1]
	v_and_b32_e32 v12, 0xffffff80, v12
	v_sub_u32_e32 v12, v12, v108
	v_add_u32_e32 v50, 0x6f, v12
	v_not_b32_e32 v12, v38
	v_or_b32_e32 v13, 0x80000000, v38
	v_cmp_gt_i32_e64 s[0:1], 0, v38
	v_max_u32_e32 v16, v19, v18
	v_min_u32_e32 v18, v19, v18
	v_cndmask_b32_e64 v12, v13, v12, s[0:1]
	v_and_b32_e32 v12, 0xffffff80, v12
	v_sub_u32_e32 v12, v12, v108
	v_add_u32_e32 v20, 0x5f, v12
	v_not_b32_e32 v12, v42
	v_or_b32_e32 v13, 0x80000000, v42
	v_cmp_gt_i32_e64 s[0:1], 0, v42
	v_max_u32_e32 v9, v11, v10
	v_min_u32_e32 v10, v11, v10
	v_cndmask_b32_e64 v12, v13, v12, s[0:1]
	v_not_b32_e32 v13, v35
	v_cmp_gt_i32_e64 s[0:1], 0, v35
	v_and_b32_e32 v12, 0xffffff80, v12
	v_sub_u32_e32 v12, v12, v108
	v_cndmask_b32_e64 v13, v15, v13, s[0:1]
	v_and_b32_e32 v13, 0xffffff80, v13
	v_sub_u32_e32 v13, v13, v109
	v_add_u32_e32 v42, 0x7f, v13
	v_not_b32_e32 v13, v31
	v_or_b32_e32 v15, 0x80000000, v31
	v_cmp_gt_i32_e64 s[0:1], 0, v31
	v_add_u32_e32 v12, 0x4f, v12
	s_nop 0
	v_cndmask_b32_e64 v13, v15, v13, s[0:1]
	v_and_b32_e32 v13, 0xffffff80, v13
	v_sub_u32_e32 v13, v13, v109
	v_add_u32_e32 v51, 0x6f, v13
	v_not_b32_e32 v13, v39
	v_or_b32_e32 v15, 0x80000000, v39
	v_cmp_gt_i32_e64 s[0:1], 0, v39
	v_max_u32_e32 v28, v50, v51
	v_min_u32_e32 v50, v50, v51
	v_cndmask_b32_e64 v13, v15, v13, s[0:1]
	v_and_b32_e32 v13, 0xffffff80, v13
	v_sub_u32_e32 v13, v13, v109
	v_add_u32_e32 v21, 0x5f, v13
	v_not_b32_e32 v13, v43
	v_or_b32_e32 v15, 0x80000000, v43
	v_cmp_gt_i32_e64 s[0:1], 0, v43
	v_max_u32_e32 v19, v20, v21
	v_min_u32_e32 v20, v20, v21
	v_cndmask_b32_e64 v13, v15, v13, s[0:1]
	v_not_b32_e32 v15, v36
	v_cmp_gt_i32_e64 s[0:1], 0, v36
	v_and_b32_e32 v13, 0xffffff80, v13
	v_sub_u32_e32 v13, v13, v109
	v_cndmask_b32_e64 v15, v17, v15, s[0:1]
	v_and_b32_e32 v15, 0xffffff80, v15
	v_sub_u32_e32 v15, v15, v110
	v_add_u32_e32 v43, 0x7f, v15
	v_not_b32_e32 v15, v32
	v_or_b32_e32 v17, 0x80000000, v32
	v_cmp_gt_i32_e64 s[0:1], 0, v32
	v_add_u32_e32 v13, 0x4f, v13
	v_max_u32_e32 v11, v12, v13
	v_cndmask_b32_e64 v15, v17, v15, s[0:1]
	v_and_b32_e32 v15, 0xffffff80, v15
	v_sub_u32_e32 v15, v15, v110
	v_add_u32_e32 v52, 0x6f, v15
	v_not_b32_e32 v15, v40
	v_or_b32_e32 v17, 0x80000000, v40
	v_cmp_gt_i32_e64 s[0:1], 0, v40
	v_min_u32_e32 v12, v12, v13
	s_nop 0
	v_cndmask_b32_e64 v15, v17, v15, s[0:1]
	v_and_b32_e32 v15, 0xffffff80, v15
	v_sub_u32_e32 v15, v15, v110
	v_add_u32_e32 v23, 0x5f, v15
	v_not_b32_e32 v15, v44
	v_or_b32_e32 v17, 0x80000000, v44
	v_cmp_gt_i32_e64 s[0:1], 0, v44
	s_nop 1
	v_cndmask_b32_e64 v15, v17, v15, s[0:1]
	v_not_b32_e32 v17, v37
	v_cmp_gt_i32_e64 s[0:1], 0, v37
	v_and_b32_e32 v15, 0xffffff80, v15
	v_sub_u32_e32 v15, v15, v110
	v_cndmask_b32_e64 v17, v25, v17, s[0:1]
	v_and_b32_e32 v17, 0xffffff80, v17
	v_sub_u32_e32 v17, v17, v111
	v_add_u32_e32 v44, 0x7f, v17
	v_not_b32_e32 v17, v33
	v_or_b32_e32 v25, 0x80000000, v33
	v_cmp_gt_i32_e64 s[0:1], 0, v33
	v_add_u32_e32 v15, 0x4f, v15
	s_nop 0
	v_cndmask_b32_e64 v17, v25, v17, s[0:1]
	v_and_b32_e32 v17, 0xffffff80, v17
	v_sub_u32_e32 v17, v17, v111
	v_add_u32_e32 v53, 0x6f, v17
	v_not_b32_e32 v17, v41
	v_or_b32_e32 v25, 0x80000000, v41
	v_cmp_gt_i32_e64 s[0:1], 0, v41
	ds_read_b128 v[30:33], v104 offset:96
	ds_read_b128 v[34:37], v104 offset:160
	ds_read_b128 v[38:41], v104 offset:224
	v_cndmask_b32_e64 v17, v25, v17, s[0:1]
	v_and_b32_e32 v17, 0xffffff80, v17
	v_sub_u32_e32 v17, v17, v111
	v_add_u32_e32 v25, 0x5f, v17
	v_not_b32_e32 v17, v45
	v_cmp_gt_i32_e64 s[0:1], 0, v45
	v_or_b32_e32 v45, 0x80000000, v4
	v_max_u32_e32 v51, v53, v52
	v_cndmask_b32_e64 v17, v27, v17, s[0:1]
	v_not_b32_e32 v27, v4
	v_cmp_gt_i32_e64 s[0:1], 0, v4
	v_and_b32_e32 v17, 0xffffff80, v17
	v_sub_u32_e32 v17, v17, v111
	v_cndmask_b32_e64 v4, v45, v27, s[0:1]
	v_and_b32_e32 v4, 0xffffff80, v4
	v_sub_u32_e32 v4, v4, v112
	v_add_u32_e32 v45, 0x7f, v4
	s_waitcnt lgkmcnt(2)
	v_not_b32_e32 v4, v30
	v_or_b32_e32 v27, 0x80000000, v30
	v_cmp_gt_i32_e64 s[0:1], 0, v30
	s_waitcnt lgkmcnt(0)
	v_or_b32_e32 v30, 0x80000000, v38
	v_add_u32_e32 v17, 0x4f, v17
	v_cndmask_b32_e64 v4, v27, v4, s[0:1]
	v_and_b32_e32 v4, 0xffffff80, v4
	v_sub_u32_e32 v4, v4, v112
	v_add_u32_e32 v54, 0x6f, v4
	v_not_b32_e32 v4, v34
	v_or_b32_e32 v27, 0x80000000, v34
	v_cmp_gt_i32_e64 s[0:1], 0, v34
	v_or_b32_e32 v34, 0x80000000, v5
	v_min_u32_e32 v52, v53, v52
	v_cndmask_b32_e64 v4, v27, v4, s[0:1]
	v_and_b32_e32 v4, 0xffffff80, v4
	v_sub_u32_e32 v4, v4, v112
	v_add_u32_e32 v27, 0x5f, v4
	v_not_b32_e32 v4, v38
	v_cmp_gt_i32_e64 s[0:1], 0, v38
	v_max_u32_e32 v21, v25, v23
	v_min_u32_e32 v23, v25, v23
	v_cndmask_b32_e64 v4, v30, v4, s[0:1]
	v_not_b32_e32 v30, v5
	v_cmp_gt_i32_e64 s[0:1], 0, v5
	v_and_b32_e32 v4, 0xffffff80, v4
	v_sub_u32_e32 v4, v4, v112
	v_cndmask_b32_e64 v5, v34, v30, s[0:1]
	v_and_b32_e32 v5, 0xffffff80, v5
	v_sub_u32_e32 v5, v5, v113
	v_add_u32_e32 v55, 0x7f, v5
	v_not_b32_e32 v5, v31
	v_or_b32_e32 v30, 0x80000000, v31
	v_cmp_gt_i32_e64 s[0:1], 0, v31
	v_or_b32_e32 v31, 0x80000000, v6
	v_add_u32_e32 v4, 0x4f, v4
	v_cndmask_b32_e64 v5, v30, v5, s[0:1]
	v_and_b32_e32 v5, 0xffffff80, v5
	v_sub_u32_e32 v5, v5, v113
	v_add_u32_e32 v56, 0x6f, v5
	v_not_b32_e32 v5, v35
	v_or_b32_e32 v30, 0x80000000, v35
	v_cmp_gt_i32_e64 s[0:1], 0, v35
	v_max_u32_e32 v53, v54, v56
	v_min_u32_e32 v54, v54, v56
	v_cndmask_b32_e64 v5, v30, v5, s[0:1]
	v_and_b32_e32 v5, 0xffffff80, v5
	v_sub_u32_e32 v5, v5, v113
	v_add_u32_e32 v57, 0x5f, v5
	v_not_b32_e32 v5, v39
	v_or_b32_e32 v30, 0x80000000, v39
	v_cmp_gt_i32_e64 s[0:1], 0, v39
	v_max_u32_e32 v25, v27, v57
	v_min_u32_e32 v27, v27, v57
	v_cndmask_b32_e64 v5, v30, v5, s[0:1]
	v_not_b32_e32 v30, v6
	v_cmp_gt_i32_e64 s[0:1], 0, v6
	v_and_b32_e32 v5, 0xffffff80, v5
	v_sub_u32_e32 v5, v5, v113
	v_cndmask_b32_e64 v6, v31, v30, s[0:1]
	v_and_b32_e32 v6, 0xffffff80, v6
	v_sub_u32_e32 v6, v6, v114
	v_add_u32_e32 v58, 0x7f, v6
	v_not_b32_e32 v6, v32
	v_or_b32_e32 v30, 0x80000000, v32
	v_cmp_gt_i32_e64 s[0:1], 0, v32
	v_or_b32_e32 v31, 0x80000000, v7
	v_add_u32_e32 v5, 0x4f, v5
	v_cndmask_b32_e64 v6, v30, v6, s[0:1]
	v_and_b32_e32 v6, 0xffffff80, v6
	v_sub_u32_e32 v6, v6, v114
	v_add_u32_e32 v59, 0x6f, v6
	v_not_b32_e32 v6, v36
	v_or_b32_e32 v30, 0x80000000, v36
	v_cmp_gt_i32_e64 s[0:1], 0, v36
	v_max_u32_e32 v13, v17, v15
	v_min_u32_e32 v15, v17, v15
	v_cndmask_b32_e64 v6, v30, v6, s[0:1]
	v_and_b32_e32 v6, 0xffffff80, v6
	v_sub_u32_e32 v6, v6, v114
	v_add_u32_e32 v60, 0x5f, v6
	v_not_b32_e32 v6, v40
	v_or_b32_e32 v30, 0x80000000, v40
	v_cmp_gt_i32_e64 s[0:1], 0, v40
	v_max_u32_e32 v17, v4, v5
	v_min_u32_e32 v4, v4, v5
	v_cndmask_b32_e64 v6, v30, v6, s[0:1]
	v_not_b32_e32 v30, v7
	v_cmp_gt_i32_e64 s[0:1], 0, v7
	v_and_b32_e32 v6, 0xffffff80, v6
	v_sub_u32_e32 v6, v6, v114
	v_cndmask_b32_e64 v7, v31, v30, s[0:1]
	v_and_b32_e32 v7, 0xffffff80, v7
	v_sub_u32_e32 v7, v7, v115
	v_add_u32_e32 v61, 0x7f, v7
	v_not_b32_e32 v7, v33
	v_or_b32_e32 v30, 0x80000000, v33
	v_cmp_gt_i32_e64 s[0:1], 0, v33
	v_add_u32_e32 v6, 0x4f, v6
	s_nop 0
	v_cndmask_b32_e64 v7, v30, v7, s[0:1]
	v_and_b32_e32 v7, 0xffffff80, v7
	v_sub_u32_e32 v7, v7, v115
	v_add_u32_e32 v62, 0x6f, v7
	v_not_b32_e32 v7, v37
	v_or_b32_e32 v30, 0x80000000, v37
	v_cmp_gt_i32_e64 s[0:1], 0, v37
	v_max_u32_e32 v56, v62, v59
	v_min_u32_e32 v59, v62, v59
	v_cndmask_b32_e64 v7, v30, v7, s[0:1]
	v_and_b32_e32 v7, 0xffffff80, v7
	v_sub_u32_e32 v7, v7, v115
	v_add_u32_e32 v63, 0x5f, v7
	v_not_b32_e32 v7, v41
	v_or_b32_e32 v30, 0x80000000, v41
	v_cmp_gt_i32_e64 s[0:1], 0, v41
	v_max_u32_e32 v57, v63, v60
	v_min_u32_e32 v60, v63, v60
	v_cndmask_b32_e64 v7, v30, v7, s[0:1]
	v_cmp_gt_i32_e64 s[0:1], 0, v0
	ds_read_b128 v[30:33], v104 offset:112
	ds_read_b128 v[34:37], v104 offset:176
	ds_read_b128 v[38:41], v104 offset:240
	v_cndmask_b32_e64 v0, v65, v64, s[0:1]
	v_and_b32_e32 v0, 0xffffff80, v0
	v_sub_u32_e32 v0, v0, v116
	v_add_u32_e32 v64, 0x7f, v0
	s_waitcnt lgkmcnt(2)
	v_not_b32_e32 v0, v30
	v_or_b32_e32 v65, 0x80000000, v30
	v_cmp_gt_i32_e64 s[0:1], 0, v30
	v_and_b32_e32 v7, 0xffffff80, v7
	v_sub_u32_e32 v7, v7, v115
	v_cndmask_b32_e64 v0, v65, v0, s[0:1]
	v_and_b32_e32 v0, 0xffffff80, v0
	v_sub_u32_e32 v0, v0, v116
	v_add_u32_e32 v30, 0x6f, v0
	s_waitcnt lgkmcnt(1)
	v_not_b32_e32 v0, v34
	v_or_b32_e32 v65, 0x80000000, v34
	v_cmp_gt_i32_e64 s[0:1], 0, v34
	v_add_u32_e32 v7, 0x4f, v7
	v_max_u32_e32 v5, v7, v6
	v_cndmask_b32_e64 v0, v65, v0, s[0:1]
	v_and_b32_e32 v0, 0xffffff80, v0
	v_sub_u32_e32 v0, v0, v116
	v_add_u32_e32 v34, 0x5f, v0
	s_waitcnt lgkmcnt(0)
	v_not_b32_e32 v0, v38
	v_or_b32_e32 v65, 0x80000000, v38
	v_cmp_gt_i32_e64 s[0:1], 0, v38
	v_not_b32_e32 v38, v1
	v_min_u32_e32 v6, v7, v6
	v_cndmask_b32_e64 v0, v65, v0, s[0:1]
	v_or_b32_e32 v65, 0x80000000, v1
	v_cmp_gt_i32_e64 s[0:1], 0, v1
	v_and_b32_e32 v0, 0xffffff80, v0
	v_sub_u32_e32 v0, v0, v116
	v_cndmask_b32_e64 v1, v65, v38, s[0:1]
	v_and_b32_e32 v1, 0xffffff80, v1
	v_sub_u32_e32 v1, v1, v117
	v_add_u32_e32 v38, 0x7f, v1
	v_not_b32_e32 v1, v31
	v_or_b32_e32 v65, 0x80000000, v31
	v_cmp_gt_i32_e64 s[0:1], 0, v31
	v_add_u32_e32 v0, 0x4f, v0
	s_nop 0
	v_cndmask_b32_e64 v1, v65, v1, s[0:1]
	v_and_b32_e32 v1, 0xffffff80, v1
	v_sub_u32_e32 v1, v1, v117
	v_add_u32_e32 v31, 0x6f, v1
	v_not_b32_e32 v1, v35
	v_or_b32_e32 v65, 0x80000000, v35
	v_cmp_gt_i32_e64 s[0:1], 0, v35
	v_max_u32_e32 v62, v30, v31
	v_min_u32_e32 v30, v30, v31
	v_cndmask_b32_e64 v1, v65, v1, s[0:1]
	v_and_b32_e32 v1, 0xffffff80, v1
	v_sub_u32_e32 v1, v1, v117
	v_add_u32_e32 v35, 0x5f, v1
	v_not_b32_e32 v1, v39
	v_or_b32_e32 v65, 0x80000000, v39
	v_cmp_gt_i32_e64 s[0:1], 0, v39
	v_not_b32_e32 v39, v2
	v_max_u32_e32 v63, v34, v35
	v_cndmask_b32_e64 v1, v65, v1, s[0:1]
	v_or_b32_e32 v65, 0x80000000, v2
	v_cmp_gt_i32_e64 s[0:1], 0, v2
	v_and_b32_e32 v1, 0xffffff80, v1
	v_sub_u32_e32 v1, v1, v117
	v_cndmask_b32_e64 v2, v65, v39, s[0:1]
	v_not_b32_e32 v39, v32
	v_or_b32_e32 v65, 0x80000000, v32
	v_cmp_gt_i32_e64 s[0:1], 0, v32
	v_and_b32_e32 v2, 0xffffff80, v2
	v_sub_u32_e32 v2, v2, v118
	v_cndmask_b32_e64 v32, v65, v39, s[0:1]
	v_not_b32_e32 v39, v36
	v_or_b32_e32 v65, 0x80000000, v36
	v_cmp_gt_i32_e64 s[0:1], 0, v36
	v_and_b32_e32 v32, 0xffffff80, v32
	v_sub_u32_e32 v32, v32, v118
	v_cndmask_b32_e64 v36, v65, v39, s[0:1]
	v_not_b32_e32 v39, v40
	v_or_b32_e32 v65, 0x80000000, v40
	v_cmp_gt_i32_e64 s[0:1], 0, v40
	v_not_b32_e32 v40, v3
	v_and_b32_e32 v36, 0xffffff80, v36
	v_cndmask_b32_e64 v39, v65, v39, s[0:1]
	v_or_b32_e32 v65, 0x80000000, v3
	v_cmp_gt_i32_e64 s[0:1], 0, v3
	v_and_b32_e32 v39, 0xffffff80, v39
	v_sub_u32_e32 v36, v36, v118
	v_cndmask_b32_e64 v3, v65, v40, s[0:1]
	v_not_b32_e32 v40, v33
	v_or_b32_e32 v65, 0x80000000, v33
	v_cmp_gt_i32_e64 s[0:1], 0, v33
	v_and_b32_e32 v3, 0xffffff80, v3
	v_sub_u32_e32 v39, v39, v118
	v_cndmask_b32_e64 v33, v65, v40, s[0:1]
	v_not_b32_e32 v40, v37
	v_or_b32_e32 v65, 0x80000000, v37
	v_cmp_gt_i32_e64 s[0:1], 0, v37
	v_and_b32_e32 v33, 0xffffff80, v33
	v_sub_u32_e32 v3, v3, v119
	v_cndmask_b32_e64 v37, v65, v40, s[0:1]
	v_not_b32_e32 v40, v41
	v_or_b32_e32 v65, 0x80000000, v41
	v_cmp_gt_i32_e64 s[0:1], 0, v41
	v_and_b32_e32 v37, 0xffffff80, v37
	v_sub_u32_e32 v33, v33, v119
	v_cndmask_b32_e64 v40, v65, v40, s[0:1]
	v_and_b32_e32 v40, 0xffffff80, v40
	v_sub_u32_e32 v37, v37, v119
	v_sub_u32_e32 v40, v40, v119
	v_add_u32_e32 v1, 0x4f, v1
	v_add_u32_e32 v2, 0x7f, v2
	v_add_u32_e32 v32, 0x6f, v32
	v_add_u32_e32 v36, 0x5f, v36
	v_add_u32_e32 v39, 0x4f, v39
	v_add_u32_e32 v3, 0x7f, v3
	v_add_u32_e32 v33, 0x6f, v33
	v_add_u32_e32 v37, 0x5f, v37
	v_add_u32_e32 v40, 0x4f, v40
	v_max_u32_e32 v41, v46, v47
	v_min_u32_e32 v46, v46, v47
	v_max_u32_e32 v47, v49, v48
	v_min_u32_e32 v48, v49, v48
	v_max_u32_e32 v49, v29, v42
	v_min_u32_e32 v29, v29, v42
	v_max_u32_e32 v42, v44, v43
	v_min_u32_e32 v43, v44, v43
	v_max_u32_e32 v44, v45, v55
	v_min_u32_e32 v45, v45, v55
	v_max_u32_e32 v55, v61, v58
	v_min_u32_e32 v58, v61, v58
	v_max_u32_e32 v61, v64, v38
	v_min_u32_e32 v38, v64, v38
	v_max_u32_e32 v64, v3, v2
	v_min_u32_e32 v2, v3, v2
	v_max_u32_e32 v31, v33, v32
	v_min_u32_e32 v32, v33, v32
	v_min_u32_e32 v34, v34, v35
	v_max_u32_e32 v35, v37, v36
	v_min_u32_e32 v36, v37, v36
	v_max_u32_e32 v7, v0, v1
	v_min_u32_e32 v0, v0, v1
	v_max_u32_e32 v1, v40, v39
	v_min_u32_e32 v39, v40, v39
	v_max_u32_e32 v3, v41, v48
	v_min_u32_e32 v41, v41, v48
	v_max_u32_e32 v48, v46, v47
	v_min_u32_e32 v46, v46, v47
	v_max_u32_e32 v47, v43, v49
	v_min_u32_e32 v43, v43, v49
	v_max_u32_e32 v49, v42, v29
	v_min_u32_e32 v29, v42, v29
	v_max_u32_e32 v42, v44, v58
	v_min_u32_e32 v44, v44, v58
	v_max_u32_e32 v58, v45, v55
	v_min_u32_e32 v45, v45, v55
	v_max_u32_e32 v55, v2, v61
	v_min_u32_e32 v2, v2, v61
	v_max_u32_e32 v61, v64, v38
	v_min_u32_e32 v38, v64, v38
	v_max_u32_e32 v33, v72, v26
	v_min_u32_e32 v26, v72, v26
	v_max_u32_e32 v72, v22, v24
	v_min_u32_e32 v22, v22, v24
	v_max_u32_e32 v24, v52, v28
	v_min_u32_e32 v28, v52, v28
	v_max_u32_e32 v52, v51, v50
	v_min_u32_e32 v50, v51, v50
	v_max_u32_e32 v51, v53, v59
	v_min_u32_e32 v53, v53, v59
	v_max_u32_e32 v59, v54, v56
	v_min_u32_e32 v54, v54, v56
	v_max_u32_e32 v56, v32, v62
	v_min_u32_e32 v32, v32, v62
	v_max_u32_e32 v62, v31, v30
	v_min_u32_e32 v30, v31, v30
	v_max_u32_e32 v37, v80, v18
	v_min_u32_e32 v18, v80, v18
	v_max_u32_e32 v80, v14, v16
	v_min_u32_e32 v14, v14, v16
	v_max_u32_e32 v16, v23, v19
	v_min_u32_e32 v19, v23, v19
	v_max_u32_e32 v23, v21, v20
	v_min_u32_e32 v20, v21, v20
	v_max_u32_e32 v21, v25, v60
	v_min_u32_e32 v25, v25, v60
	v_max_u32_e32 v60, v27, v57
	v_min_u32_e32 v27, v27, v57
	v_max_u32_e32 v57, v36, v63
	v_min_u32_e32 v36, v36, v63
	v_max_u32_e32 v63, v35, v34
	v_min_u32_e32 v34, v35, v34
	v_max_u32_e32 v40, v88, v10
	v_min_u32_e32 v10, v88, v10
	v_max_u32_e32 v88, v8, v9
	v_min_u32_e32 v8, v8, v9
	v_max_u32_e32 v9, v15, v11
	v_min_u32_e32 v11, v15, v11
	v_max_u32_e32 v15, v13, v12
	v_min_u32_e32 v12, v13, v12
	v_max_u32_e32 v13, v17, v6
	v_min_u32_e32 v6, v17, v6
	v_max_u32_e32 v17, v4, v5
	v_min_u32_e32 v4, v4, v5
	v_max_u32_e32 v5, v39, v7
	v_min_u32_e32 v7, v39, v7
	v_max_u32_e32 v39, v1, v0
	v_min_u32_e32 v0, v1, v0
	v_max_u32_e32 v64, v3, v48
	v_min_u32_e32 v3, v3, v48
	v_max_u32_e32 v48, v41, v46
	v_min_u32_e32 v41, v41, v46
	v_max_u32_e32 v46, v29, v43
	v_min_u32_e32 v29, v29, v43
	v_max_u32_e32 v43, v49, v47
	v_min_u32_e32 v47, v49, v47
	v_max_u32_e32 v49, v42, v58
	v_min_u32_e32 v42, v42, v58
	v_max_u32_e32 v58, v44, v45
	v_min_u32_e32 v44, v44, v45
	v_max_u32_e32 v45, v38, v2
	v_min_u32_e32 v2, v38, v2
	v_max_u32_e32 v38, v61, v55
	v_min_u32_e32 v55, v61, v55
	v_max_u32_e32 v31, v33, v72
	v_min_u32_e32 v33, v33, v72
	v_max_u32_e32 v72, v26, v22
	v_min_u32_e32 v22, v26, v22
	v_max_u32_e32 v26, v50, v28
	v_min_u32_e32 v28, v50, v28
	v_max_u32_e32 v50, v52, v24
	v_min_u32_e32 v24, v52, v24
	v_max_u32_e32 v52, v51, v59
	v_min_u32_e32 v51, v51, v59
	v_max_u32_e32 v59, v53, v54
	v_min_u32_e32 v53, v53, v54
	v_max_u32_e32 v54, v30, v32
	v_min_u32_e32 v30, v30, v32
	v_max_u32_e32 v32, v62, v56
	v_min_u32_e32 v56, v62, v56
	v_max_u32_e32 v35, v37, v80
	v_min_u32_e32 v37, v37, v80
	v_max_u32_e32 v80, v18, v14
	v_min_u32_e32 v14, v18, v14
	v_max_u32_e32 v18, v20, v19
	v_min_u32_e32 v19, v20, v19
	v_max_u32_e32 v20, v23, v16
	v_min_u32_e32 v16, v23, v16
	v_max_u32_e32 v23, v21, v60
	v_min_u32_e32 v21, v21, v60
	v_max_u32_e32 v60, v25, v27
	v_min_u32_e32 v25, v25, v27
	v_max_u32_e32 v27, v34, v36
	v_min_u32_e32 v34, v34, v36
	v_max_u32_e32 v36, v63, v57
	v_min_u32_e32 v57, v63, v57
	v_max_u32_e32 v1, v40, v88
	v_min_u32_e32 v40, v40, v88
	v_max_u32_e32 v88, v10, v8
	v_min_u32_e32 v8, v10, v8
	v_max_u32_e32 v10, v12, v11
	v_min_u32_e32 v11, v12, v11
	v_max_u32_e32 v12, v15, v9
	v_min_u32_e32 v9, v15, v9
	v_max_u32_e32 v15, v13, v17
	v_min_u32_e32 v13, v13, v17
	v_max_u32_e32 v17, v6, v4
	v_min_u32_e32 v4, v6, v4
	v_max_u32_e32 v6, v0, v7
	v_min_u32_e32 v0, v0, v7
	v_max_u32_e32 v7, v39, v5
	v_min_u32_e32 v5, v39, v5
	v_max_u32_e32 v61, v64, v29
	v_min_u32_e32 v29, v64, v29
	v_max_u32_e32 v64, v3, v46
	v_min_u32_e32 v3, v3, v46
	v_max_u32_e32 v46, v48, v47
	v_min_u32_e32 v47, v48, v47
	v_max_u32_e32 v48, v41, v43
	v_min_u32_e32 v41, v41, v43
	v_max_u32_e32 v43, v2, v49
	v_min_u32_e32 v2, v2, v49
	v_max_u32_e32 v49, v45, v42
	v_min_u32_e32 v42, v45, v42
	v_max_u32_e32 v45, v55, v58
	v_min_u32_e32 v55, v55, v58
	v_max_u32_e32 v58, v38, v44
	v_min_u32_e32 v38, v38, v44
	v_max_u32_e32 v62, v31, v28
	v_min_u32_e32 v28, v31, v28
	v_max_u32_e32 v31, v33, v26
	v_min_u32_e32 v26, v33, v26
	v_max_u32_e32 v33, v72, v24
	v_min_u32_e32 v24, v72, v24
	v_max_u32_e32 v72, v22, v50
	v_min_u32_e32 v22, v22, v50
	v_max_u32_e32 v50, v30, v52
	v_min_u32_e32 v30, v30, v52
	v_max_u32_e32 v52, v54, v51
	v_min_u32_e32 v51, v54, v51
	v_max_u32_e32 v54, v56, v59
	v_min_u32_e32 v56, v56, v59
	v_max_u32_e32 v59, v32, v53
	v_min_u32_e32 v32, v32, v53
	v_max_u32_e32 v63, v35, v19
	v_min_u32_e32 v19, v35, v19
	v_max_u32_e32 v35, v37, v18
	v_min_u32_e32 v18, v37, v18
	v_max_u32_e32 v37, v80, v16
	v_min_u32_e32 v16, v80, v16
	v_max_u32_e32 v80, v14, v20
	v_min_u32_e32 v14, v14, v20
	v_max_u32_e32 v20, v34, v23
	v_min_u32_e32 v23, v34, v23
	v_max_u32_e32 v34, v27, v21
	v_min_u32_e32 v21, v27, v21
	v_max_u32_e32 v27, v57, v60
	v_min_u32_e32 v57, v57, v60
	v_max_u32_e32 v60, v36, v25
	v_min_u32_e32 v25, v36, v25
	v_max_u32_e32 v39, v1, v11
	v_min_u32_e32 v1, v1, v11
	v_max_u32_e32 v11, v40, v10
	v_min_u32_e32 v10, v40, v10
	v_max_u32_e32 v40, v88, v9
	v_min_u32_e32 v9, v88, v9
	v_max_u32_e32 v88, v8, v12
	v_min_u32_e32 v8, v8, v12
	v_max_u32_e32 v12, v0, v15
	v_min_u32_e32 v0, v0, v15
	v_max_u32_e32 v15, v6, v13
	v_min_u32_e32 v6, v6, v13
	v_max_u32_e32 v13, v5, v17
	v_min_u32_e32 v5, v5, v17
	v_max_u32_e32 v17, v7, v4
	v_min_u32_e32 v4, v7, v4
	v_max_u32_e32 v44, v61, v46
	v_min_u32_e32 v46, v61, v46
	v_max_u32_e32 v61, v64, v48
	v_min_u32_e32 v48, v64, v48
	v_max_u32_e32 v64, v29, v47
	v_min_u32_e32 v29, v29, v47
	v_max_u32_e32 v47, v3, v41
	v_min_u32_e32 v3, v3, v41
	v_max_u32_e32 v41, v55, v2
	v_min_u32_e32 v2, v55, v2
	v_max_u32_e32 v55, v38, v42
	v_min_u32_e32 v38, v38, v42
	v_max_u32_e32 v42, v45, v43
	v_min_u32_e32 v43, v45, v43
	v_max_u32_e32 v45, v58, v49
	v_min_u32_e32 v49, v58, v49
	v_max_u32_e32 v53, v62, v33
	v_min_u32_e32 v33, v62, v33
	v_max_u32_e32 v62, v31, v72
	v_min_u32_e32 v31, v31, v72
	v_max_u32_e32 v72, v28, v24
	v_min_u32_e32 v24, v28, v24
	v_max_u32_e32 v28, v26, v22
	v_min_u32_e32 v22, v26, v22
	v_max_u32_e32 v26, v56, v30
	v_min_u32_e32 v30, v56, v30
	v_max_u32_e32 v56, v32, v51
	v_min_u32_e32 v32, v32, v51
	v_max_u32_e32 v51, v54, v50
	v_min_u32_e32 v50, v54, v50
	v_max_u32_e32 v54, v59, v52
	v_min_u32_e32 v52, v59, v52
	v_max_u32_e32 v36, v63, v37
	v_min_u32_e32 v37, v63, v37
	v_max_u32_e32 v63, v35, v80
	v_min_u32_e32 v35, v35, v80
	v_max_u32_e32 v80, v19, v16
	v_min_u32_e32 v16, v19, v16
	v_max_u32_e32 v19, v18, v14
	v_min_u32_e32 v14, v18, v14
	v_max_u32_e32 v18, v57, v23
	v_min_u32_e32 v23, v57, v23
	v_max_u32_e32 v57, v25, v21
	v_min_u32_e32 v21, v25, v21
	v_max_u32_e32 v25, v27, v20
	v_min_u32_e32 v20, v27, v20
	v_max_u32_e32 v27, v60, v34
	v_min_u32_e32 v34, v60, v34
	v_max_u32_e32 v7, v39, v40
	v_min_u32_e32 v39, v39, v40
	v_max_u32_e32 v40, v11, v88
	v_min_u32_e32 v11, v11, v88
	v_max_u32_e32 v88, v1, v9
	v_min_u32_e32 v1, v1, v9
	v_max_u32_e32 v9, v10, v8
	v_min_u32_e32 v8, v10, v8
	v_max_u32_e32 v10, v5, v0
	v_min_u32_e32 v0, v5, v0
	v_max_u32_e32 v5, v4, v6
	v_min_u32_e32 v4, v4, v6
	v_max_u32_e32 v6, v13, v12
	v_min_u32_e32 v12, v13, v12
	v_max_u32_e32 v13, v17, v15
	v_min_u32_e32 v15, v17, v15
	v_max_u32_e32 v58, v44, v61
	v_min_u32_e32 v44, v44, v61
	v_max_u32_e32 v61, v46, v48
	v_min_u32_e32 v46, v46, v48
	v_max_u32_e32 v48, v64, v47
	v_min_u32_e32 v47, v64, v47
	v_max_u32_e32 v64, v29, v3
	v_min_u32_e32 v3, v29, v3
	v_max_u32_e32 v29, v38, v2
	v_min_u32_e32 v2, v38, v2
	v_max_u32_e32 v38, v55, v41
	v_min_u32_e32 v41, v55, v41
	v_max_u32_e32 v55, v49, v43
	v_min_u32_e32 v43, v49, v43
	v_max_u32_e32 v49, v45, v42
	v_min_u32_e32 v42, v45, v42
	v_max_u32_e32 v59, v53, v62
	v_min_u32_e32 v53, v53, v62
	v_max_u32_e32 v62, v33, v31
	v_min_u32_e32 v31, v33, v31
	v_max_u32_e32 v33, v72, v28
	v_min_u32_e32 v28, v72, v28
	v_max_u32_e32 v72, v24, v22
	v_min_u32_e32 v22, v24, v22
	v_max_u32_e32 v24, v32, v30
	v_min_u32_e32 v30, v32, v30
	v_max_u32_e32 v32, v56, v26
	v_min_u32_e32 v26, v56, v26
	v_max_u32_e32 v56, v52, v50
	v_min_u32_e32 v50, v52, v50
	v_max_u32_e32 v52, v54, v51
	v_min_u32_e32 v51, v54, v51
	v_max_u32_e32 v60, v36, v63
	v_min_u32_e32 v36, v36, v63
	v_max_u32_e32 v63, v37, v35
	v_min_u32_e32 v35, v37, v35
	v_max_u32_e32 v37, v80, v19
	v_min_u32_e32 v19, v80, v19
	v_max_u32_e32 v80, v16, v14
	v_min_u32_e32 v14, v16, v14
	v_max_u32_e32 v16, v21, v23
	v_min_u32_e32 v21, v21, v23
	v_max_u32_e32 v23, v57, v18
	v_min_u32_e32 v18, v57, v18
	v_max_u32_e32 v57, v34, v20
	v_min_u32_e32 v20, v34, v20
	v_max_u32_e32 v34, v27, v25
	v_min_u32_e32 v25, v27, v25
	v_max_u32_e32 v17, v7, v40
	v_min_u32_e32 v7, v7, v40
	v_max_u32_e32 v40, v39, v11
	v_min_u32_e32 v11, v39, v11
	v_max_u32_e32 v39, v88, v9
	v_min_u32_e32 v9, v88, v9
	v_max_u32_e32 v88, v1, v8
	v_min_u32_e32 v1, v1, v8
	v_max_u32_e32 v8, v4, v0
	v_min_u32_e32 v0, v4, v0
	v_max_u32_e32 v4, v5, v10
	v_min_u32_e32 v5, v5, v10
	v_max_u32_e32 v10, v15, v12
	v_min_u32_e32 v12, v15, v12
	v_max_u32_e32 v15, v13, v6
	v_min_u32_e32 v6, v13, v6
	v_max_u32_e32 v45, v58, v2
	v_min_u32_e32 v2, v58, v2
	v_max_u32_e32 v58, v44, v29
	v_min_u32_e32 v29, v44, v29
	v_max_u32_e32 v44, v61, v41
	v_min_u32_e32 v41, v61, v41
	v_max_u32_e32 v61, v46, v38
	v_min_u32_e32 v38, v46, v38
	v_max_u32_e32 v46, v48, v43
	v_min_u32_e32 v43, v48, v43
	v_max_u32_e32 v48, v47, v55
	v_min_u32_e32 v47, v47, v55
	v_max_u32_e32 v55, v64, v42
	v_min_u32_e32 v42, v64, v42
	v_max_u32_e32 v64, v3, v49
	v_min_u32_e32 v3, v3, v49
	v_max_u32_e32 v54, v59, v30
	v_min_u32_e32 v30, v59, v30
	v_max_u32_e32 v59, v53, v24
	v_min_u32_e32 v24, v53, v24
	v_max_u32_e32 v53, v62, v26
	v_min_u32_e32 v26, v62, v26
	v_max_u32_e32 v62, v31, v32
	v_min_u32_e32 v31, v31, v32
	v_max_u32_e32 v32, v33, v50
	v_min_u32_e32 v33, v33, v50
	v_max_u32_e32 v50, v28, v56
	v_min_u32_e32 v28, v28, v56
	v_max_u32_e32 v56, v72, v51
	v_min_u32_e32 v51, v72, v51
	v_max_u32_e32 v72, v22, v52
	v_min_u32_e32 v22, v22, v52
	v_max_u32_e32 v27, v60, v21
	v_min_u32_e32 v21, v60, v21
	v_max_u32_e32 v60, v36, v16
	v_min_u32_e32 v16, v36, v16
	v_max_u32_e32 v36, v63, v18
	v_min_u32_e32 v18, v63, v18
	v_max_u32_e32 v63, v35, v23
	v_min_u32_e32 v23, v35, v23
	v_max_u32_e32 v35, v37, v20
	v_min_u32_e32 v20, v37, v20
	v_max_u32_e32 v37, v19, v57
	v_min_u32_e32 v19, v19, v57
	v_max_u32_e32 v57, v80, v25
	v_min_u32_e32 v25, v80, v25
	v_max_u32_e32 v80, v14, v34
	v_min_u32_e32 v14, v14, v34
	v_max_u32_e32 v13, v17, v0
	v_min_u32_e32 v0, v17, v0
	v_max_u32_e32 v17, v7, v8
	v_min_u32_e32 v7, v7, v8
	v_max_u32_e32 v8, v40, v5
	v_min_u32_e32 v5, v40, v5
	v_max_u32_e32 v40, v11, v4
	v_min_u32_e32 v4, v11, v4
	v_max_u32_e32 v11, v39, v12
	v_min_u32_e32 v12, v39, v12
	v_max_u32_e32 v39, v9, v10
	v_min_u32_e32 v9, v9, v10
	v_max_u32_e32 v10, v88, v6
	v_min_u32_e32 v6, v88, v6
	v_max_u32_e32 v88, v1, v15
	v_min_u32_e32 v1, v1, v15
	v_max_u32_e32 v49, v45, v46
	v_min_u32_e32 v45, v45, v46
	v_max_u32_e32 v46, v58, v48
	v_min_u32_e32 v48, v58, v48
	v_max_u32_e32 v58, v44, v55
	v_min_u32_e32 v44, v44, v55
	v_max_u32_e32 v55, v61, v64
	v_min_u32_e32 v61, v61, v64
	v_max_u32_e32 v64, v2, v43
	v_min_u32_e32 v43, v2, v43
	v_max_u32_e32 v65, v29, v47
	v_min_u32_e32 v29, v29, v47
	v_max_u32_e32 v47, v41, v42
	v_min_u32_e32 v41, v41, v42
	v_max_u32_e32 v42, v38, v3
	v_min_u32_e32 v38, v38, v3
	v_max_u32_e32 v52, v54, v32
	v_min_u32_e32 v32, v54, v32
	v_max_u32_e32 v54, v59, v50
	v_min_u32_e32 v50, v59, v50
	v_max_u32_e32 v59, v53, v56
	v_min_u32_e32 v53, v53, v56
	v_max_u32_e32 v56, v62, v72
	v_min_u32_e32 v62, v62, v72
	v_max_u32_e32 v72, v30, v33
	v_min_u32_e32 v30, v30, v33
	v_max_u32_e32 v33, v24, v28
	v_min_u32_e32 v24, v24, v28
	v_max_u32_e32 v28, v26, v51
	v_min_u32_e32 v26, v26, v51
	v_max_u32_e32 v51, v31, v22
	v_min_u32_e32 v22, v31, v22
	v_max_u32_e32 v34, v27, v35
	v_min_u32_e32 v27, v27, v35
	v_max_u32_e32 v35, v60, v37
	v_min_u32_e32 v37, v60, v37
	v_max_u32_e32 v60, v36, v57
	v_min_u32_e32 v36, v36, v57
	v_max_u32_e32 v57, v63, v80
	v_min_u32_e32 v63, v63, v80
	v_max_u32_e32 v80, v21, v20
	v_min_u32_e32 v20, v21, v20
	v_max_u32_e32 v21, v16, v19
	v_min_u32_e32 v16, v16, v19
	v_max_u32_e32 v19, v18, v25
	v_min_u32_e32 v18, v18, v25
	v_max_u32_e32 v25, v23, v14
	v_min_u32_e32 v14, v23, v14
	v_max_u32_e32 v15, v13, v11
	v_min_u32_e32 v11, v13, v11
	v_max_u32_e32 v13, v17, v39
	v_min_u32_e32 v17, v17, v39
	v_max_u32_e32 v39, v8, v10
	v_min_u32_e32 v8, v8, v10
	v_max_u32_e32 v10, v40, v88
	v_min_u32_e32 v40, v40, v88
	v_max_u32_e32 v88, v0, v12
	v_min_u32_e32 v0, v0, v12
	v_max_u32_e32 v12, v7, v9
	v_min_u32_e32 v7, v7, v9
	v_max_u32_e32 v9, v5, v6
	v_min_u32_e32 v5, v5, v6
	v_max_u32_e32 v6, v4, v1
	v_min_u32_e32 v1, v4, v1
	v_max_u32_e32 v2, v49, v58
	v_min_u32_e32 v49, v49, v58
	v_max_u32_e32 v3, v46, v55
	v_min_u32_e32 v46, v46, v55
	v_max_u32_e32 v55, v45, v44
	v_min_u32_e32 v44, v45, v44
	v_max_u32_e32 v45, v48, v61
	v_min_u32_e32 v48, v48, v61
	v_max_u32_e32 v58, v64, v47
	v_min_u32_e32 v47, v64, v47
	v_max_u32_e32 v61, v65, v42
	v_min_u32_e32 v42, v65, v42
	v_max_u32_e32 v64, v43, v41
	v_min_u32_e32 v41, v43, v41
	v_max_u32_e32 v43, v29, v38
	v_min_u32_e32 v29, v29, v38
	v_max_u32_e32 v31, v52, v59
	v_min_u32_e32 v52, v52, v59
	v_max_u32_e32 v59, v54, v56
	v_min_u32_e32 v54, v54, v56
	v_max_u32_e32 v56, v32, v53
	v_min_u32_e32 v32, v32, v53
	v_max_u32_e32 v53, v50, v62
	v_min_u32_e32 v50, v50, v62
	v_max_u32_e32 v62, v72, v28
	v_min_u32_e32 v28, v72, v28
	v_max_u32_e32 v72, v33, v51
	v_min_u32_e32 v33, v33, v51
	v_max_u32_e32 v51, v30, v26
	v_min_u32_e32 v26, v30, v26
	v_max_u32_e32 v30, v24, v22
	v_min_u32_e32 v22, v24, v22
	v_max_u32_e32 v23, v34, v60
	v_min_u32_e32 v34, v34, v60
	v_max_u32_e32 v60, v35, v57
	v_min_u32_e32 v35, v35, v57
	v_max_u32_e32 v57, v27, v36
	v_min_u32_e32 v27, v27, v36
	v_max_u32_e32 v36, v37, v63
	v_min_u32_e32 v37, v37, v63
	v_max_u32_e32 v63, v80, v19
	v_min_u32_e32 v19, v80, v19
	v_max_u32_e32 v80, v21, v25
	v_min_u32_e32 v21, v21, v25
	v_max_u32_e32 v25, v20, v18
	v_min_u32_e32 v18, v20, v18
	v_max_u32_e32 v20, v16, v14
	v_min_u32_e32 v14, v16, v14
	v_max_u32_e32 v4, v15, v39
	v_min_u32_e32 v15, v15, v39
	v_max_u32_e32 v39, v13, v10
	v_min_u32_e32 v10, v13, v10
	v_max_u32_e32 v13, v11, v8
	v_min_u32_e32 v8, v11, v8
	v_max_u32_e32 v11, v17, v40
	v_min_u32_e32 v17, v17, v40
	v_max_u32_e32 v40, v88, v9
	v_min_u32_e32 v9, v88, v9
	v_max_u32_e32 v88, v12, v6
	v_min_u32_e32 v6, v12, v6
	v_max_u32_e32 v12, v0, v5
	v_min_u32_e32 v0, v0, v5
	v_max_u32_e32 v5, v7, v1
	v_min_u32_e32 v1, v7, v1
	v_min_u32_e32 v38, v2, v3
	v_min_u32_e32 v65, v49, v46
	v_min_u32_e32 v66, v55, v45
	v_min_u32_e32 v67, v44, v48
	v_min_u32_e32 v68, v58, v61
	v_min_u32_e32 v69, v47, v42
	v_min_u32_e32 v70, v64, v43
	v_min_u32_e32 v71, v41, v29
	v_min_u32_e32 v24, v31, v59
	v_min_u32_e32 v73, v52, v54
	v_min_u32_e32 v74, v56, v53
	v_min_u32_e32 v75, v32, v50
	v_min_u32_e32 v76, v62, v72
	v_min_u32_e32 v77, v28, v33
	v_min_u32_e32 v78, v51, v30
	v_min_u32_e32 v79, v26, v22
	v_min_u32_e32 v16, v23, v60
	v_min_u32_e32 v81, v34, v35
	v_min_u32_e32 v82, v57, v36
	v_min_u32_e32 v83, v27, v37
	v_min_u32_e32 v84, v63, v80
	v_min_u32_e32 v85, v19, v21
	v_min_u32_e32 v86, v25, v20
	v_min_u32_e32 v87, v18, v14
	v_min_u32_e32 v7, v4, v39
	v_min_u32_e32 v89, v15, v10
	v_min_u32_e32 v90, v13, v11
	v_min_u32_e32 v91, v8, v17
	v_min_u32_e32 v92, v40, v88
	v_min_u32_e32 v93, v9, v6
	v_min_u32_e32 v94, v12, v5
	v_min_u32_e32 v95, v0, v1
	v_max3_u32 v23, v23, v60, v95
	v_max3_u32 v22, v38, v26, v22
	v_max3_u32 v0, v16, v0, v1
	v_max3_u32 v1, v49, v46, v78
	v_max3_u32 v16, v34, v35, v94
	v_max3_u32 v26, v65, v51, v30
	v_max3_u32 v5, v81, v12, v5
	v_max3_u32 v12, v55, v45, v77
	v_max3_u32 v30, v57, v36, v93
	v_max3_u32 v28, v66, v28, v33
	v_max3_u32 v6, v82, v9, v6
	v_max3_u32 v9, v44, v48, v76
	v_max3_u32 v27, v27, v37, v92
	v_max3_u32 v33, v67, v62, v72
	v_max3_u32 v34, v83, v40, v88
	v_max3_u32 v35, v63, v80, v91
	v_max3_u32 v32, v68, v32, v50
	v_max3_u32 v8, v84, v8, v17
	v_max3_u32 v17, v47, v42, v74
	v_max3_u32 v19, v19, v21, v90
	v_max3_u32 v21, v69, v56, v53
	v_max3_u32 v11, v85, v13, v11
	v_max3_u32 v13, v64, v43, v73
	v_max3_u32 v20, v25, v20, v89
	v_max3_u32 v25, v70, v52, v54
	v_max3_u32 v10, v86, v15, v10
	v_max3_u32 v15, v41, v29, v24
	v_max3_u32 v7, v18, v14, v7
	v_max3_u32 v14, v71, v31, v59
	v_max3_u32 v4, v87, v4, v39
	v_max3_u32 v18, v58, v61, v75
	v_max3_u32 v2, v2, v3, v79
	v_max_u32_e32 v3, v2, v18
	v_min_u32_e32 v2, v2, v18
	v_max_u32_e32 v18, v22, v32
	v_min_u32_e32 v22, v22, v32
	v_max_u32_e32 v24, v1, v17
	v_min_u32_e32 v1, v1, v17
	v_max_u32_e32 v17, v26, v21
	v_min_u32_e32 v21, v26, v21
	v_max_u32_e32 v26, v12, v13
	v_min_u32_e32 v12, v12, v13
	v_max_u32_e32 v13, v28, v25
	v_min_u32_e32 v25, v28, v25
	v_max_u32_e32 v28, v9, v15
	v_min_u32_e32 v9, v9, v15
	v_max_u32_e32 v15, v33, v14
	v_min_u32_e32 v14, v33, v14
	v_max_u32_e32 v40, v23, v35
	v_min_u32_e32 v23, v23, v35
	v_max_u32_e32 v35, v0, v8
	v_min_u32_e32 v0, v0, v8
	v_max_u32_e32 v8, v16, v19
	v_min_u32_e32 v16, v16, v19
	v_max_u32_e32 v19, v5, v11
	v_min_u32_e32 v5, v5, v11
	v_max_u32_e32 v11, v30, v20
	v_min_u32_e32 v20, v30, v20
	v_max_u32_e32 v30, v6, v10
	v_min_u32_e32 v6, v6, v10
	v_max_u32_e32 v10, v27, v7
	v_min_u32_e32 v7, v27, v7
	v_max_u32_e32 v27, v34, v4
	v_min_u32_e32 v4, v34, v4
	v_max_u32_e32 v29, v3, v26
	v_min_u32_e32 v3, v3, v26
	v_max_u32_e32 v26, v18, v13
	v_min_u32_e32 v13, v18, v13
	v_max_u32_e32 v18, v24, v28
	v_min_u32_e32 v24, v24, v28
	v_max_u32_e32 v28, v17, v15
	v_min_u32_e32 v15, v17, v15
	v_max_u32_e32 v17, v2, v12
	v_min_u32_e32 v2, v2, v12
	v_max_u32_e32 v12, v22, v25
	v_min_u32_e32 v22, v22, v25
	v_max_u32_e32 v25, v1, v9
	v_min_u32_e32 v1, v1, v9
	v_max_u32_e32 v9, v21, v14
	v_min_u32_e32 v14, v21, v14
	v_max_u32_e32 v34, v40, v11
	v_min_u32_e32 v11, v40, v11
	v_max_u32_e32 v40, v35, v30
	v_min_u32_e32 v30, v35, v30
	v_max_u32_e32 v35, v8, v10
	v_min_u32_e32 v8, v8, v10
	v_max_u32_e32 v10, v19, v27
	v_min_u32_e32 v19, v19, v27
	v_max_u32_e32 v27, v23, v20
	v_min_u32_e32 v20, v23, v20
	v_max_u32_e32 v23, v0, v6
	v_min_u32_e32 v0, v0, v6
	v_max_u32_e32 v6, v16, v7
	v_min_u32_e32 v7, v16, v7
	v_max_u32_e32 v16, v5, v4
	v_min_u32_e32 v4, v5, v4
	v_max_u32_e32 v21, v29, v18
	v_min_u32_e32 v18, v29, v18
	v_max_u32_e32 v29, v26, v28
	v_min_u32_e32 v26, v26, v28
	v_max_u32_e32 v28, v3, v24
	v_min_u32_e32 v3, v3, v24
	v_max_u32_e32 v24, v13, v15
	v_min_u32_e32 v13, v13, v15
	v_max_u32_e32 v15, v17, v25
	v_min_u32_e32 v17, v17, v25
	v_max_u32_e32 v25, v12, v9
	v_min_u32_e32 v9, v12, v9
	v_max_u32_e32 v12, v2, v1
	v_min_u32_e32 v1, v2, v1
	v_max_u32_e32 v2, v22, v14
	v_min_u32_e32 v14, v22, v14
	v_max_u32_e32 v5, v34, v35
	v_min_u32_e32 v34, v34, v35
	v_max_u32_e32 v35, v40, v10
	v_min_u32_e32 v10, v40, v10
	v_max_u32_e32 v40, v11, v8
	v_min_u32_e32 v8, v11, v8
	v_max_u32_e32 v11, v30, v19
	v_min_u32_e32 v19, v30, v19
	v_max_u32_e32 v30, v27, v6
	v_min_u32_e32 v6, v27, v6
	v_max_u32_e32 v27, v23, v16
	v_min_u32_e32 v16, v23, v16
	v_max_u32_e32 v23, v20, v7
	v_min_u32_e32 v7, v20, v7
	v_max_u32_e32 v20, v0, v4
	v_min_u32_e32 v0, v0, v4
	v_min_u32_e32 v22, v21, v29
	v_min_u32_e32 v31, v18, v26
	v_min_u32_e32 v32, v28, v24
	v_min_u32_e32 v33, v3, v13
	v_min_u32_e32 v36, v15, v25
	v_min_u32_e32 v37, v17, v9
	v_min_u32_e32 v38, v12, v2
	v_min_u32_e32 v39, v1, v14
	v_min_u32_e32 v4, v5, v35
	v_min_u32_e32 v41, v34, v10
	v_min_u32_e32 v42, v40, v11
	v_min_u32_e32 v43, v8, v19
	v_min_u32_e32 v44, v30, v27
	v_min_u32_e32 v45, v6, v16
	v_min_u32_e32 v46, v23, v20
	v_min_u32_e32 v47, v7, v0
	v_max3_u32 v0, v22, v7, v0
	v_max3_u32 v7, v18, v26, v46
	v_max3_u32 v18, v31, v23, v20
	v_max3_u32 v20, v28, v24, v45
	v_max3_u32 v6, v32, v6, v16
	v_max3_u32 v3, v3, v13, v44
	v_max3_u32 v13, v33, v30, v27
	v_max3_u32 v8, v36, v8, v19
	v_max3_u32 v9, v17, v9, v42
	v_max3_u32 v11, v37, v40, v11
	v_max3_u32 v2, v12, v2, v41
	v_max3_u32 v10, v38, v34, v10
	v_max3_u32 v1, v1, v14, v4
	v_max3_u32 v4, v39, v5, v35
	v_max3_u32 v5, v15, v25, v43
	v_max3_u32 v12, v21, v29, v47
	v_max_u32_e32 v14, v12, v5
	v_min_u32_e32 v5, v12, v5
	v_max_u32_e32 v12, v0, v8
	v_min_u32_e32 v0, v0, v8
	v_max_u32_e32 v8, v7, v9
	v_min_u32_e32 v7, v7, v9
	v_max_u32_e32 v9, v18, v11
	v_max_u32_e32 v15, v20, v2
	v_max_u32_e32 v16, v6, v10
	v_min_u32_e32 v6, v6, v10
	v_max_u32_e32 v10, v3, v1
	v_min_u32_e32 v1, v3, v1
	v_max_u32_e32 v3, v13, v4
	v_min_u32_e32 v11, v18, v11
	v_min_u32_e32 v2, v20, v2
	v_min_u32_e32 v4, v13, v4
	v_max_u32_e32 v13, v14, v15
	v_min_u32_e32 v14, v14, v15
	v_max_u32_e32 v15, v12, v16
	v_min_u32_e32 v12, v12, v16
	v_max_u32_e32 v16, v8, v10
	v_min_u32_e32 v8, v8, v10
	v_max_u32_e32 v10, v9, v3
	v_min_u32_e32 v3, v9, v3
	v_max_u32_e32 v9, v5, v2
	v_min_u32_e32 v2, v5, v2
	v_max_u32_e32 v5, v0, v6
	v_min_u32_e32 v0, v0, v6
	v_max_u32_e32 v6, v7, v1
	v_min_u32_e32 v1, v7, v1
	v_max_u32_e32 v7, v11, v4
	v_min_u32_e32 v4, v11, v4
	v_max_u32_e32 v11, v13, v16
	v_min_u32_e32 v13, v13, v16
	v_max_u32_e32 v16, v15, v10
	v_cmp_lt_i32_e64 s[0:1], v120, v121
	v_min_u32_e32 v10, v15, v10
	v_max_u32_e32 v15, v14, v8
	v_min_u32_e32 v8, v14, v8
	v_max_u32_e32 v14, v12, v3
	v_min_u32_e32 v3, v12, v3
	v_max_u32_e32 v18, v2, v1
	v_min_u32_e32 v19, v2, v1
	v_max_u32_e32 v20, v0, v4
	v_min_u32_e32 v21, v0, v4
	v_max_u32_e32 v0, v11, v16
	v_min_u32_e32 v1, v11, v16
	v_cndmask_b32_e64 v16, v215, v120, s[0:1]
	v_max_u32_e32 v12, v9, v6
	v_min_u32_e32 v6, v9, v6
	v_max_u32_e32 v9, v5, v7
	v_min_u32_e32 v17, v5, v7
	v_max_u32_e32 v5, v15, v14
	v_min_u32_e32 v7, v15, v14
	v_max_u32_e32 v11, v8, v3
	v_min_u32_e32 v14, v8, v3
	v_max_u32_e32 v8, v19, v21
	v_lshlrev_b32_e32 v16, 2, v16
	v_max_u32_e32 v2, v13, v10
	v_min_u32_e32 v4, v13, v10
	v_max_u32_e32 v3, v12, v9
	v_min_u32_e32 v15, v12, v9
	v_max_u32_e32 v10, v18, v20
	v_min_u32_e32 v9, v18, v20
	ds_bpermute_b32 v18, v16, v8
	v_max_u32_e32 v13, v6, v17
	v_min_u32_e32 v12, v6, v17
	v_min_u32_e32 v6, v19, v21
	ds_bpermute_b32 v19, v16, v9
	s_waitcnt lgkmcnt(1)
	v_max_u32_e32 v18, v1, v18
	ds_bpermute_b32 v20, v16, v10
	ds_bpermute_b32 v21, v16, v12
	ds_bpermute_b32 v22, v16, v13
	ds_bpermute_b32 v23, v16, v15
	ds_bpermute_b32 v24, v16, v3
	ds_bpermute_b32 v1, v16, v1
	ds_bpermute_b32 v17, v16, v6
	s_waitcnt lgkmcnt(7)
	v_max_u32_e32 v19, v2, v19
	s_waitcnt lgkmcnt(6)
	v_max_u32_e32 v20, v4, v20
	s_waitcnt lgkmcnt(5)
	v_max_u32_e32 v21, v5, v21
	s_waitcnt lgkmcnt(4)
	v_max_u32_e32 v22, v7, v22
	s_waitcnt lgkmcnt(3)
	v_max_u32_e32 v23, v11, v23
	s_waitcnt lgkmcnt(2)
	v_max_u32_e32 v24, v14, v24
	ds_bpermute_b32 v14, v16, v14
	ds_bpermute_b32 v11, v16, v11
	ds_bpermute_b32 v7, v16, v7
	ds_bpermute_b32 v5, v16, v5
	ds_bpermute_b32 v4, v16, v4
	ds_bpermute_b32 v2, v16, v2
	s_waitcnt lgkmcnt(7)
	v_max_u32_e32 v1, v8, v1
	ds_bpermute_b32 v8, v16, v0
	s_waitcnt lgkmcnt(5)
	v_max_u32_e32 v11, v15, v11
	s_waitcnt lgkmcnt(4)
	v_max_u32_e32 v7, v13, v7
	s_waitcnt lgkmcnt(3)
	v_max_u32_e32 v5, v12, v5
	s_waitcnt lgkmcnt(2)
	v_max_u32_e32 v4, v10, v4
	s_waitcnt lgkmcnt(1)
	v_max_u32_e32 v2, v9, v2
	s_waitcnt lgkmcnt(0)
	v_max_u32_e32 v6, v6, v8
	v_max_u32_e32 v3, v3, v14
	v_max_u32_e32 v0, v0, v17
	v_max_u32_e32 v8, v0, v3
	v_min_u32_e32 v0, v0, v3
	v_max_u32_e32 v3, v18, v11
	v_min_u32_e32 v9, v18, v11
	v_max_u32_e32 v10, v19, v7
	v_min_u32_e32 v7, v19, v7
	v_max_u32_e32 v11, v20, v5
	v_min_u32_e32 v5, v20, v5
	v_max_u32_e32 v12, v21, v4
	v_min_u32_e32 v4, v21, v4
	v_max_u32_e32 v13, v22, v2
	v_min_u32_e32 v2, v22, v2
	v_max_u32_e32 v14, v23, v1
	v_min_u32_e32 v1, v23, v1
	v_max_u32_e32 v15, v24, v6
	v_min_u32_e32 v6, v24, v6
	v_max_u32_e32 v16, v8, v12
	v_min_u32_e32 v8, v8, v12
	v_max_u32_e32 v12, v3, v13
	v_min_u32_e32 v3, v3, v13
	v_max_u32_e32 v13, v10, v14
	v_min_u32_e32 v10, v10, v14
	v_max_u32_e32 v14, v11, v15
	v_min_u32_e32 v11, v11, v15
	v_max_u32_e32 v15, v0, v4
	v_min_u32_e32 v0, v0, v4
	v_max_u32_e32 v4, v9, v2
	v_min_u32_e32 v2, v9, v2
	v_max_u32_e32 v9, v7, v1
	v_min_u32_e32 v1, v7, v1
	v_max_u32_e32 v7, v5, v6
	v_min_u32_e32 v5, v5, v6
	v_max_u32_e32 v6, v16, v13
	v_min_u32_e32 v13, v16, v13
	v_max_u32_e32 v16, v12, v14
	v_min_u32_e32 v12, v12, v14
	v_max_u32_e32 v14, v8, v10
	v_min_u32_e32 v8, v8, v10
	v_max_u32_e32 v10, v3, v11
	v_min_u32_e32 v3, v3, v11
	v_max_u32_e32 v11, v15, v9
	v_min_u32_e32 v9, v15, v9
	v_max_u32_e32 v15, v4, v7
	v_min_u32_e32 v4, v4, v7
	v_max_u32_e32 v7, v0, v1
	v_min_u32_e32 v0, v0, v1
	v_max_u32_e32 v1, v2, v5
	v_min_u32_e32 v2, v2, v5
	v_max_u32_e32 v5, v6, v16
	v_min_u32_e32 v6, v6, v16
	v_max_u32_e32 v16, v13, v12
	v_min_u32_e32 v12, v13, v12
	v_max_u32_e32 v13, v14, v10
	v_min_u32_e32 v10, v14, v10
	v_max_u32_e32 v14, v8, v3
	v_min_u32_e32 v17, v8, v3
	v_max_u32_e32 v3, v11, v15
	v_min_u32_e32 v8, v11, v15
	v_max_u32_e32 v11, v9, v4
	v_max_u32_e32 v15, v0, v2
	v_min_u32_e32 v18, v0, v2
	v_cndmask_b32_e32 v2, v11, v16, vcc
	v_min_u32_e32 v4, v9, v4
	v_max_u32_e32 v9, v7, v1
	v_min_u32_e32 v7, v7, v1
	v_cndmask_b32_e32 v1, v8, v6, vcc
	v_bitop3_b32 v6, v2, s16, v2 bitop3:0xc
	v_cndmask_b32_e32 v0, v3, v5, vcc
	v_bitop3_b32 v3, v1, s16, v1 bitop3:0xc
	v_lshl_add_u32 v2, v6, 2, v102
	v_lshlrev_b32_e32 v6, 16, v6
	v_lshl_add_u32 v1, v3, 2, v102
	v_lshl_or_b32 v6, v3, 8, v6
	v_cndmask_b32_e32 v3, v4, v12, vcc
	v_bitop3_b32 v4, v3, s16, v3 bitop3:0xc
	v_bitop3_b32 v5, v0, s16, v0 bitop3:0xc
	v_lshl_add_u32 v3, v4, 2, v102
	v_lshlrev_b32_e32 v4, 24, v4
	v_or3_b32 v8, v6, v4, v5
	v_cndmask_b32_e32 v6, v15, v14, vcc
	v_lshl_add_u32 v0, v5, 2, v102
	v_cndmask_b32_e32 v5, v7, v10, vcc
	v_bitop3_b32 v10, v6, s16, v6 bitop3:0xc
	v_bitop3_b32 v7, v5, s16, v5 bitop3:0xc
	v_lshl_add_u32 v6, v10, 2, v102
	v_lshlrev_b32_e32 v10, 16, v10
	v_cndmask_b32_e32 v4, v9, v13, vcc
	v_lshl_add_u32 v5, v7, 2, v102
	v_lshl_or_b32 v10, v7, 8, v10
	v_cndmask_b32_e32 v7, v18, v17, vcc
	v_bitop3_b32 v9, v4, s16, v4 bitop3:0xc
	v_bitop3_b32 v11, v7, s16, v7 bitop3:0xc
	ds_read_b32 v0, v0
	ds_read_b32 v1, v1
	ds_read_b32 v2, v2
	ds_read_b32 v3, v3
	ds_read_b32 v5, v5
	ds_read_b32 v6, v6
	v_lshl_add_u32 v4, v9, 2, v102
	v_lshl_add_u32 v7, v11, 2, v102
	s_lshl_b64 s[0:1], s[12:13], 15
	ds_read_b32 v4, v4
	ds_read_b32 v7, v7
	s_add_u32 s0, s0, s10
	v_lshlrev_b32_e32 v11, 24, v11
	s_addc_u32 s1, s1, s11
	v_or3_b32 v9, v10, v11, v9
	v_lshl_add_u64 v[10:11], s[0:1], 0, v[96:97]
	v_lshl_add_u64 v[12:13], v[10:11], 2, s[22:23]
	s_add_i32 s17, s17, s2
	s_waitcnt lgkmcnt(4)
	global_store_dwordx4 v[12:13], v[0:3], off
	s_waitcnt lgkmcnt(0)
	global_store_dwordx4 v[12:13], v[4:7], off offset:16
	s_cmpk_lt_i32 s17, 0x1000
	v_lshl_add_u64 v[0:1], s[24:25], 0, v[10:11]
	global_store_dwordx2 v[0:1], v[8:9], off
	s_cbranch_scc1 .LBB0_631
.LBB0_632:
.Lq_tail:
	s_cmp_eq_u32 s33, 0
	s_cbranch_scc1 .Lq_tnofin
	s_waitcnt vmcnt(0)
	v_mov_b32_e32 v204, v199
	v_mov_b32_e32 v205, v199
	v_mov_b32_e32 v206, v199
	v_mov_b32_e32 v207, v199
	v_max_f32_e64 v208, |v179|, |v179|
	v_max_f32_e64 v209, |v178|, |v178|
	v_max_f32_e64 v210, |v175|, |v175|
	v_max_f32_e64 v211, |v174|, |v174|
	v_max_f32_e64 v212, |v171|, |v171|
	v_max_f32_e64 v213, |v170|, |v170|
	v_max_f32_e64 v216, |v167|, |v167|
	v_max_f32_e64 v217, |v166|, |v166|
	v_max_f32_e32 v208, v209, v208
	v_max_f32_e32 v209, v211, v210
	v_max_f32_e32 v210, v213, v212
	v_max_f32_e32 v211, v217, v216
	v_max3_f32 v208, |v176|, |v177|, v208
	v_max3_f32 v209, |v172|, |v173|, v209
	v_max3_f32 v210, |v168|, |v169|, v210
	v_max3_f32 v211, |v164|, |v165|, v211
	v_max3_f32 v208, v208, 0, v209
	v_max3_f32 v208, v208, v210, v211
	v_mov_b32_e32 v209, v208
	s_nop 1
	v_mov_b32_dpp v209, v209 quad_perm:[1,0,3,2] row_mask:0xf bank_mask:0xf
	v_max_f32_e32 v209, v209, v209
	v_max_f32_e32 v208, v208, v209
	v_mov_b32_e32 v209, v208
	s_nop 1
	v_mov_b32_dpp v209, v209 quad_perm:[2,3,0,1] row_mask:0xf bank_mask:0xf
	v_max_f32_e32 v209, v209, v209
	v_max_f32_e32 v208, v208, v209
	v_mov_b32_e32 v209, v208
	s_nop 1
	v_mov_b32_dpp v209, v209 row_half_mirror row_mask:0xf bank_mask:0xf
	v_max_f32_e32 v209, v209, v209
	v_max_f32_e32 v208, v208, v209
	v_mov_b32_e32 v209, v208
	s_nop 1
	v_mov_b32_dpp v209, v209 row_mirror row_mask:0xf bank_mask:0xf
	v_max_f32_e32 v209, v209, v209
	v_max_f32_e32 v208, v208, v209
	v_mov_b32_e32 v209, v208
	s_nop 1
	v_mov_b32_dpp v209, v209 row_bcast:15 row_mask:0xa bank_mask:0xf
	v_max_f32_e32 v209, v209, v209
	v_max_f32_e32 v208, v208, v209
	v_mov_b32_e32 v209, v208
	s_nop 1
	v_mov_b32_dpp v209, v209 row_bcast:31 row_mask:0xc bank_mask:0xf
	v_max_f32_e32 v209, v209, v209
	v_max_f32_e32 v208, v208, v209
	s_nop 0
	v_readlane_b32 s40, v208, 63
	s_nop 1
	v_div_scale_f32 v208, s[42:43], s40, s40, v200
	v_rcp_f32_e32 v209, v208
	v_mov_b32_e32 v210, s40
	s_mov_b32 s42, 0x43600000
	v_div_scale_f32 v210, vcc, s42, v210, s42
	v_fma_f32 v211, -v208, v209, 1.0
	v_fmac_f32_e32 v209, v211, v209
	v_mul_f32_e32 v211, v210, v209
	v_fma_f32 v212, -v208, v211, v210
	v_fmac_f32_e32 v211, v212, v209
	v_fma_f32 v208, -v208, v211, v210
	v_div_fmas_f32 v208, v208, v209, v211
	v_div_fixup_f32 v208, v208, s40, v200
	v_cmp_gt_f32_e64 vcc, s40, 0
	s_nop 1
	v_cndmask_b32_e32 v208, 1.0, v208, vcc
	v_mul_f32_e32 v176, v176, v208
	v_mul_f32_e32 v177, v177, v208
	v_mul_f32_e32 v172, v172, v208
	v_mul_f32_e32 v173, v173, v208
	v_mul_f32_e32 v168, v168, v208
	v_mul_f32_e32 v169, v169, v208
	v_mul_f32_e32 v164, v164, v208
	v_mul_f32_e32 v165, v165, v208
	v_cvt_pk_fp8_f32 v204, v176, v177
	v_cvt_pk_fp8_f32 v205, v172, v173
	v_cvt_pk_fp8_f32 v206, v168, v169
	v_cvt_pk_fp8_f32 v207, v164, v165
	v_mul_f32_e32 v178, v178, v208
	v_mul_f32_e32 v179, v179, v208
	v_mul_f32_e32 v174, v174, v208
	v_mul_f32_e32 v175, v175, v208
	v_mul_f32_e32 v170, v170, v208
	v_mul_f32_e32 v171, v171, v208
	v_mul_f32_e32 v166, v166, v208
	v_mul_f32_e32 v167, v167, v208
	v_cvt_pk_fp8_f32 v204, v178, v179 op_sel:[0,0,1]
	v_cvt_pk_fp8_f32 v205, v174, v175 op_sel:[0,0,1]
	v_cvt_pk_fp8_f32 v206, v170, v171 op_sel:[0,0,1]
	v_cvt_pk_fp8_f32 v207, v166, v167 op_sel:[0,0,1]
	s_lshl_b32 s46, s39, 10
	s_add_u32 s48, s94, 0x28c0000
	s_addc_u32 s49, s95, 0
	s_add_u32 s48, s48, s46
	s_addc_u32 s49, s49, 0
	global_store_dwordx4 v197, v[204:207], s[48:49]
	v_mul_f32_e32 v218, s40, v201
	v_cndmask_b32_e32 v218, 1.0, v218, vcc
	s_lshl_b32 s46, s39, 2
	s_add_u32 s48, s94, 0x38c0000
	s_addc_u32 s49, s95, 0
	s_add_u32 s48, s48, s46
	s_addc_u32 s49, s49, 0
	s_mov_b64 s[44:45], exec
	s_mov_b64 exec, 1
	global_store_dword v199, v218, s[48:49]
	s_mov_b64 exec, s[44:45]
	v_mov_b32_e32 v204, v199
	v_mov_b32_e32 v205, v199
	v_max_f32_e64 v208, |v195|, |v195|
	v_max_f32_e64 v206, |v194|, |v194|
	v_max_f32_e64 v207, |v191|, |v191|
	v_max_f32_e64 v209, |v190|, |v190|
	v_max_f32_e64 v210, |v187|, |v187|
	v_max_f32_e64 v211, |v186|, |v186|
	v_max_f32_e64 v212, |v183|, |v183|
	v_max_f32_e64 v213, |v182|, |v182|
	v_max_f32_e32 v208, v206, v208
	v_max_f32_e32 v206, v209, v207
	v_max_f32_e32 v207, v211, v210
	v_max_f32_e32 v209, v213, v212
	v_max3_f32 v208, |v192|, |v193|, v208
	v_max3_f32 v206, |v188|, |v189|, v206
	v_max3_f32 v207, |v184|, |v185|, v207
	v_max3_f32 v209, |v180|, |v181|, v209
	v_max3_f32 v208, v208, 0, v206
	v_max3_f32 v208, v208, v207, v209
	v_mov_b32_e32 v206, v208
	s_nop 1
	v_mov_b32_dpp v206, v206 quad_perm:[1,0,3,2] row_mask:0xf bank_mask:0xf
	v_max_f32_e32 v206, v206, v206
	v_max_f32_e32 v208, v208, v206
	v_mov_b32_e32 v206, v208
	s_nop 1
	v_mov_b32_dpp v206, v206 quad_perm:[2,3,0,1] row_mask:0xf bank_mask:0xf
	v_max_f32_e32 v206, v206, v206
	v_max_f32_e32 v208, v208, v206
	v_mov_b32_e32 v206, v208
	s_nop 1
	v_mov_b32_dpp v206, v206 row_half_mirror row_mask:0xf bank_mask:0xf
	v_max_f32_e32 v206, v206, v206
	v_max_f32_e32 v208, v208, v206
	v_mov_b32_e32 v206, v208
	s_nop 1
	v_mov_b32_dpp v206, v206 row_mirror row_mask:0xf bank_mask:0xf
	v_max_f32_e32 v206, v206, v206
	v_max_f32_e32 v208, v208, v206
	v_mov_b32_e32 v206, v208
	s_nop 1
	v_mov_b32_dpp v206, v206 row_bcast:15 row_mask:0xa bank_mask:0xf
	v_max_f32_e32 v206, v206, v206
	v_max_f32_e32 v208, v208, v206
	v_mov_b32_e32 v206, v208
	s_nop 1
	v_mov_b32_dpp v206, v206 row_bcast:31 row_mask:0xc bank_mask:0xf
	v_max_f32_e32 v206, v206, v206
	v_max_f32_e32 v208, v208, v206
	s_nop 0
	v_readlane_b32 s40, v208, 63
	s_nop 1
	v_div_scale_f32 v208, s[42:43], s40, s40, v202
	v_rcp_f32_e32 v206, v208
	v_mov_b32_e32 v207, s40
	s_mov_b32 s42, 0x40c00000
	v_div_scale_f32 v207, vcc, s42, v207, s42
	v_fma_f32 v209, -v208, v206, 1.0
	v_fmac_f32_e32 v206, v209, v206
	v_mul_f32_e32 v209, v207, v206
	v_fma_f32 v210, -v208, v209, v207
	v_fmac_f32_e32 v209, v210, v206
	v_fma_f32 v208, -v208, v209, v207
	v_div_fmas_f32 v208, v208, v206, v209
	v_div_fixup_f32 v208, v208, s40, v202
	v_cmp_gt_f32_e64 vcc, s40, 0
	s_nop 1
	v_cndmask_b32_e32 v208, 1.0, v208, vcc
	v_mul_f32_e32 v192, v192, v208
	v_mul_f32_e32 v193, v193, v208
	v_mul_f32_e32 v184, v184, v208
	v_mul_f32_e32 v185, v185, v208
	v_mul_f32_e32 v194, v194, v208
	v_mul_f32_e32 v195, v195, v208
	v_mul_f32_e32 v186, v186, v208
	v_mul_f32_e32 v187, v187, v208
	v_cvt_scalef32_pk_fp4_f32 v204, v192, v193, 1.0
	v_cvt_scalef32_pk_fp4_f32 v205, v184, v185, 1.0
	v_mul_f32_e32 v188, v188, v208
	v_mul_f32_e32 v189, v189, v208
	v_mul_f32_e32 v180, v180, v208
	v_mul_f32_e32 v181, v181, v208
	v_cvt_scalef32_pk_fp4_f32 v204, v194, v195, 1.0 op_sel:[0,0,1,0]
	v_cvt_scalef32_pk_fp4_f32 v205, v186, v187, 1.0 op_sel:[0,0,1,0]
	v_mul_f32_e32 v190, v190, v208
	v_mul_f32_e32 v191, v191, v208
	v_mul_f32_e32 v182, v182, v208
	v_mul_f32_e32 v183, v183, v208
	v_cvt_scalef32_pk_fp4_f32 v204, v188, v189, 1.0 op_sel:[0,0,0,1]
	v_cvt_scalef32_pk_fp4_f32 v205, v180, v181, 1.0 op_sel:[0,0,0,1]
	v_cvt_scalef32_pk_fp4_f32 v204, v190, v191, 1.0 op_sel:[0,0,1,1]
	v_cvt_scalef32_pk_fp4_f32 v205, v182, v183, 1.0 op_sel:[0,0,1,1]
	s_lshl_b32 s46, s39, 9
	s_add_u32 s48, s94, 0x38d0000
	s_addc_u32 s49, s95, 0
	s_add_u32 s48, s48, s46
	s_addc_u32 s49, s49, 0
	global_store_dwordx2 v198, v[204:205], s[48:49]
	v_mul_f32_e32 v218, s40, v203
	v_cndmask_b32_e32 v218, 1.0, v218, vcc
	s_lshl_b32 s46, s39, 2
	s_add_u32 s48, s94, 0x48d0000
	s_addc_u32 s49, s95, 0
	s_add_u32 s48, s48, s46
	s_addc_u32 s49, s49, 0
	s_mov_b64 s[44:45], exec
	s_mov_b64 exec, 1
	global_store_dword v199, v218, s[48:49]
	s_mov_b64 exec, s[44:45]
.Lq_tnofin:
	s_mov_b32 s33, 0
	s_cmp_ge_u32 s38, 0x4000
	s_cbranch_scc1 .Lq_tdone
	s_lshl_b32 s46, s38, 12
	s_add_u32 s48, s34, s46
	s_addc_u32 s49, s35, 0
	global_load_dwordx4 v[176:179], v196, s[48:49]
	global_load_dwordx4 v[172:175], v196, s[48:49] offset:16
	global_load_dwordx4 v[168:171], v196, s[48:49] offset:32
	global_load_dwordx4 v[164:167], v196, s[48:49] offset:48
	s_add_u32 s48, s36, s46
	s_addc_u32 s49, s37, 0
	global_load_dwordx4 v[192:195], v196, s[48:49]
	global_load_dwordx4 v[188:191], v196, s[48:49] offset:16
	global_load_dwordx4 v[184:187], v196, s[48:49] offset:32
	global_load_dwordx4 v[180:183], v196, s[48:49] offset:48
	s_mov_b32 s39, s38
	s_add_u32 s38, s38, s32
	s_mov_b32 s33, 1
	s_branch .Lq_tail
